# K-loop back-edge SALU (counter/pointer increments, exit compare) rotated ahead of the last barrier in all GEMM loops
# speedup vs baseline: 1.0019x; 1.0019x over previous
.Lsp_p1:
.LBB0_277:
	ds_read_b128 v[148:151], v145
	ds_read_b128 v[152:155], v145 offset:1024
	ds_read_b128 v[156:159], v145 offset:2048
	ds_read_b128 v[160:163], v145 offset:3072
	ds_read_b128 v[166:169], v146
	ds_read_b128 v[170:173], v146 offset:1024
	ds_read_b128 v[174:177], v146 offset:2048
	ds_read_b128 v[178:181], v146 offset:3072
	s_add_u32 s28, s26, 0xfff80080
	s_addc_u32 s29, s27, -1
	s_cmp_eq_u32 s50, 28
	s_cselect_b32 s31, s2, s29
	s_cselect_b32 s30, s13, s28
	s_cselect_b32 s29, s15, s33
	s_cselect_b32 s28, s23, s25
	v_lshl_add_u64 v[214:215], s[26:27], 0, v[138:139]
	s_add_i32 m0, s37, 0xc000
	ds_read_b128 v[182:185], v147
	ds_read_b128 v[186:189], v147 offset:1024
	ds_read_b128 v[190:193], v147 offset:2048
	ds_read_b128 v[194:197], v147 offset:3072
	ds_read_b128 v[198:201], v147 offset:4096
	ds_read_b128 v[202:205], v147 offset:5120
	ds_read_b128 v[206:209], v147 offset:6144
	ds_read_b128 v[210:213], v147 offset:7168
	global_load_lds_dwordx4 v[214:215], off
	v_lshl_add_u64 v[214:215], s[26:27], 0, v[140:141]
	s_add_i32 m0, s37, 0xe000
	s_nop 0
	global_load_lds_dwordx4 v[214:215], off
	s_waitcnt vmcnt(8)
	s_waitcnt lgkmcnt(0)
	s_barrier
	s_nop 0
	s_waitcnt lgkmcnt(0)
	v_mfma_f32_16x16x32_bf16 v[126:129], v[148:151], v[182:185], v[126:129]
	v_mfma_f32_16x16x32_bf16 v[122:125], v[156:159], v[182:185], v[122:125]
	v_mfma_f32_16x16x32_bf16 v[110:113], v[148:151], v[190:193], v[110:113]
	v_mfma_f32_16x16x32_bf16 v[106:109], v[156:159], v[190:193], v[106:109]
	v_mfma_f32_16x16x32_bf16 v[94:97], v[148:151], v[198:201], v[94:97]
	v_mfma_f32_16x16x32_bf16 v[90:93], v[156:159], v[198:201], v[90:93]
	v_mfma_f32_16x16x32_bf16 v[78:81], v[148:151], v[206:209], v[78:81]
	v_mfma_f32_16x16x32_bf16 v[74:77], v[156:159], v[206:209], v[74:77]
	v_mfma_f32_16x16x32_bf16 v[126:129], v[152:155], v[186:189], v[126:129]
	v_mfma_f32_16x16x32_bf16 v[122:125], v[160:163], v[186:189], v[122:125]
	v_mfma_f32_16x16x32_bf16 v[110:113], v[152:155], v[194:197], v[110:113]
	v_mfma_f32_16x16x32_bf16 v[106:109], v[160:163], v[194:197], v[106:109]
	v_mfma_f32_16x16x32_bf16 v[94:97], v[152:155], v[202:205], v[94:97]
	v_mfma_f32_16x16x32_bf16 v[90:93], v[160:163], v[202:205], v[90:93]
	v_mfma_f32_16x16x32_bf16 v[78:81], v[152:155], v[210:213], v[78:81]
	v_mfma_f32_16x16x32_bf16 v[74:77], v[160:163], v[210:213], v[74:77]
	s_nop 0
	s_nop 0
	v_mfma_f32_16x16x32_bf16 v[118:121], v[166:169], v[182:185], v[118:121]
	v_mfma_f32_16x16x32_bf16 v[114:117], v[174:177], v[182:185], v[114:117]
	v_mfma_f32_16x16x32_bf16 v[102:105], v[166:169], v[190:193], v[102:105]
	v_mfma_f32_16x16x32_bf16 v[98:101], v[174:177], v[190:193], v[98:101]
	v_mfma_f32_16x16x32_bf16 v[86:89], v[166:169], v[198:201], v[86:89]
	v_mfma_f32_16x16x32_bf16 v[82:85], v[174:177], v[198:201], v[82:85]
	v_mfma_f32_16x16x32_bf16 v[70:73], v[166:169], v[206:209], v[70:73]
	v_mfma_f32_16x16x32_bf16 v[66:69], v[174:177], v[206:209], v[66:69]
	v_mfma_f32_16x16x32_bf16 v[118:121], v[170:173], v[186:189], v[118:121]
	v_mfma_f32_16x16x32_bf16 v[114:117], v[178:181], v[186:189], v[114:117]
	v_mfma_f32_16x16x32_bf16 v[102:105], v[170:173], v[194:197], v[102:105]
	v_mfma_f32_16x16x32_bf16 v[98:101], v[178:181], v[194:197], v[98:101]
	v_mfma_f32_16x16x32_bf16 v[86:89], v[170:173], v[202:205], v[86:89]
	v_mfma_f32_16x16x32_bf16 v[82:85], v[178:181], v[202:205], v[82:85]
	v_mfma_f32_16x16x32_bf16 v[70:73], v[170:173], v[210:213], v[70:73]
	v_mfma_f32_16x16x32_bf16 v[66:69], v[178:181], v[210:213], v[66:69]
	s_nop 0
	s_barrier
	s_add_i32 s51, s48, s36
	v_lshl_add_u64 v[214:215], s[28:29], 0, v[132:133]
	s_mov_b32 m0, s51
	ds_read_b128 v[182:185], v147 offset:16384
	ds_read_b128 v[186:189], v147 offset:17408
	ds_read_b128 v[190:193], v147 offset:18432
	ds_read_b128 v[194:197], v147 offset:19456
	ds_read_b128 v[198:201], v147 offset:20480
	ds_read_b128 v[202:205], v147 offset:21504
	ds_read_b128 v[206:209], v147 offset:22528
	ds_read_b128 v[210:213], v147 offset:23552
	global_load_lds_dwordx4 v[214:215], off
	s_add_i32 m0, s51, 0x2000
	s_add_u32 s52, s28, 0x80000
	v_lshl_add_u64 v[216:217], s[28:29], 0, v[136:137]
	s_addc_u32 s53, s29, 0
	s_add_i32 s51, s49, s36
	global_load_lds_dwordx4 v[216:217], off
	v_lshl_add_u64 v[218:219], s[52:53], 0, v[132:133]
	s_mov_b32 m0, s51
	v_lshl_add_u64 v[220:221], s[30:31], 0, v[134:135]
	global_load_lds_dwordx4 v[218:219], off
	v_lshl_add_u64 v[218:219], s[52:53], 0, v[136:137]
	s_add_i32 m0, s51, 0x2000
	s_nop 0
	global_load_lds_dwordx4 v[218:219], off
	v_lshl_add_u64 v[218:219], s[30:31], 0, v[130:131]
	s_mov_b32 m0, s37
	s_nop 0
	global_load_lds_dwordx4 v[218:219], off
	s_mov_b32 m0, s38
	s_nop 0
	global_load_lds_dwordx4 v[220:221], off
	s_waitcnt vmcnt(8)
	s_waitcnt lgkmcnt(0)
	s_barrier
	s_nop 0
	s_waitcnt lgkmcnt(0)
	v_mfma_f32_16x16x32_bf16 v[62:65], v[148:151], v[182:185], v[62:65]
	v_mfma_f32_16x16x32_bf16 v[58:61], v[156:159], v[182:185], v[58:61]
	v_mfma_f32_16x16x32_bf16 v[46:49], v[148:151], v[190:193], v[46:49]
	v_mfma_f32_16x16x32_bf16 v[42:45], v[156:159], v[190:193], v[42:45]
	v_mfma_f32_16x16x32_bf16 v[30:33], v[148:151], v[198:201], v[30:33]
	v_mfma_f32_16x16x32_bf16 v[26:29], v[156:159], v[198:201], v[26:29]
	v_mfma_f32_16x16x32_bf16 v[14:17], v[148:151], v[206:209], v[14:17]
	v_mfma_f32_16x16x32_bf16 v[10:13], v[156:159], v[206:209], v[10:13]
	v_mfma_f32_16x16x32_bf16 v[62:65], v[152:155], v[186:189], v[62:65]
	v_mfma_f32_16x16x32_bf16 v[58:61], v[160:163], v[186:189], v[58:61]
	v_mfma_f32_16x16x32_bf16 v[46:49], v[152:155], v[194:197], v[46:49]
	v_mfma_f32_16x16x32_bf16 v[42:45], v[160:163], v[194:197], v[42:45]
	v_mfma_f32_16x16x32_bf16 v[30:33], v[152:155], v[202:205], v[30:33]
	v_mfma_f32_16x16x32_bf16 v[26:29], v[160:163], v[202:205], v[26:29]
	v_mfma_f32_16x16x32_bf16 v[14:17], v[152:155], v[210:213], v[14:17]
	v_mfma_f32_16x16x32_bf16 v[10:13], v[160:163], v[210:213], v[10:13]
	s_nop 0
	s_nop 0
	v_mfma_f32_16x16x32_bf16 v[54:57], v[166:169], v[182:185], v[54:57]
	v_mfma_f32_16x16x32_bf16 v[50:53], v[174:177], v[182:185], v[50:53]
	v_mfma_f32_16x16x32_bf16 v[38:41], v[166:169], v[190:193], v[38:41]
	v_mfma_f32_16x16x32_bf16 v[34:37], v[174:177], v[190:193], v[34:37]
	v_mfma_f32_16x16x32_bf16 v[22:25], v[166:169], v[198:201], v[22:25]
	v_mfma_f32_16x16x32_bf16 v[18:21], v[174:177], v[198:201], v[18:21]
	v_mfma_f32_16x16x32_bf16 v[6:9], v[166:169], v[206:209], v[6:9]
	v_mfma_f32_16x16x32_bf16 v[2:5], v[174:177], v[206:209], v[2:5]
	v_mfma_f32_16x16x32_bf16 v[54:57], v[170:173], v[186:189], v[54:57]
	v_mfma_f32_16x16x32_bf16 v[50:53], v[178:181], v[186:189], v[50:53]
	v_mfma_f32_16x16x32_bf16 v[38:41], v[170:173], v[194:197], v[38:41]
	v_mfma_f32_16x16x32_bf16 v[34:37], v[178:181], v[194:197], v[34:37]
	v_mfma_f32_16x16x32_bf16 v[22:25], v[170:173], v[202:205], v[22:25]
	v_mfma_f32_16x16x32_bf16 v[18:21], v[178:181], v[202:205], v[18:21]
	v_mfma_f32_16x16x32_bf16 v[6:9], v[170:173], v[210:213], v[6:9]
	v_mfma_f32_16x16x32_bf16 v[2:5], v[178:181], v[210:213], v[2:5]
	s_nop 0
	s_barrier
	s_add_i32 s51, 0, 0x18000
	s_add_i32 s52, 0, 0x1c000
	v_add_u32_e32 v160, s51, v144
	v_add_u32_e32 v164, s52, v144
	ds_read_b128 v[148:151], v160
	ds_read_b128 v[152:155], v160 offset:1024
	ds_read_b128 v[156:159], v160 offset:2048
	ds_read_b128 v[160:163], v160 offset:3072
	ds_read_b128 v[166:169], v164
	ds_read_b128 v[170:173], v164 offset:1024
	ds_read_b128 v[174:177], v164 offset:2048
	ds_read_b128 v[178:181], v164 offset:3072
	s_add_u32 s30, s30, 0x80000
	s_addc_u32 s31, s31, 0
	s_mov_b32 m0, s39
	v_lshl_add_u64 v[222:223], s[30:31], 0, v[130:131]
	ds_read_b128 v[182:185], v147 offset:32768
	ds_read_b128 v[186:189], v147 offset:33792
	ds_read_b128 v[190:193], v147 offset:34816
	ds_read_b128 v[194:197], v147 offset:35840
	ds_read_b128 v[198:201], v147 offset:36864
	ds_read_b128 v[202:205], v147 offset:37888
	ds_read_b128 v[206:209], v147 offset:38912
	ds_read_b128 v[210:213], v147 offset:39936
	global_load_lds_dwordx4 v[222:223], off
	v_lshl_add_u64 v[222:223], s[30:31], 0, v[134:135]
	s_mov_b32 m0, s40
	s_nop 0
	global_load_lds_dwordx4 v[222:223], off
	s_waitcnt vmcnt(8)
	s_waitcnt lgkmcnt(0)
	s_barrier
	s_nop 0
	s_waitcnt lgkmcnt(0)
	v_mfma_f32_16x16x32_bf16 v[126:129], v[148:151], v[182:185], v[126:129]
	v_mfma_f32_16x16x32_bf16 v[122:125], v[156:159], v[182:185], v[122:125]
	v_mfma_f32_16x16x32_bf16 v[110:113], v[148:151], v[190:193], v[110:113]
	v_mfma_f32_16x16x32_bf16 v[106:109], v[156:159], v[190:193], v[106:109]
	v_mfma_f32_16x16x32_bf16 v[94:97], v[148:151], v[198:201], v[94:97]
	v_mfma_f32_16x16x32_bf16 v[90:93], v[156:159], v[198:201], v[90:93]
	v_mfma_f32_16x16x32_bf16 v[78:81], v[148:151], v[206:209], v[78:81]
	v_mfma_f32_16x16x32_bf16 v[74:77], v[156:159], v[206:209], v[74:77]
	v_mfma_f32_16x16x32_bf16 v[126:129], v[152:155], v[186:189], v[126:129]
	v_mfma_f32_16x16x32_bf16 v[122:125], v[160:163], v[186:189], v[122:125]
	v_mfma_f32_16x16x32_bf16 v[110:113], v[152:155], v[194:197], v[110:113]
	v_mfma_f32_16x16x32_bf16 v[106:109], v[160:163], v[194:197], v[106:109]
	v_mfma_f32_16x16x32_bf16 v[94:97], v[152:155], v[202:205], v[94:97]
	v_mfma_f32_16x16x32_bf16 v[90:93], v[160:163], v[202:205], v[90:93]
	v_mfma_f32_16x16x32_bf16 v[78:81], v[152:155], v[210:213], v[78:81]
	v_mfma_f32_16x16x32_bf16 v[74:77], v[160:163], v[210:213], v[74:77]
	s_nop 0
	s_nop 0
	v_mfma_f32_16x16x32_bf16 v[118:121], v[166:169], v[182:185], v[118:121]
	v_mfma_f32_16x16x32_bf16 v[114:117], v[174:177], v[182:185], v[114:117]
	v_mfma_f32_16x16x32_bf16 v[102:105], v[166:169], v[190:193], v[102:105]
	v_mfma_f32_16x16x32_bf16 v[98:101], v[174:177], v[190:193], v[98:101]
	v_mfma_f32_16x16x32_bf16 v[86:89], v[166:169], v[198:201], v[86:89]
	v_mfma_f32_16x16x32_bf16 v[82:85], v[174:177], v[198:201], v[82:85]
	v_mfma_f32_16x16x32_bf16 v[70:73], v[166:169], v[206:209], v[70:73]
	v_mfma_f32_16x16x32_bf16 v[66:69], v[174:177], v[206:209], v[66:69]
	v_mfma_f32_16x16x32_bf16 v[118:121], v[170:173], v[186:189], v[118:121]
	v_mfma_f32_16x16x32_bf16 v[114:117], v[178:181], v[186:189], v[114:117]
	v_mfma_f32_16x16x32_bf16 v[102:105], v[170:173], v[194:197], v[102:105]
	v_mfma_f32_16x16x32_bf16 v[98:101], v[178:181], v[194:197], v[98:101]
	v_mfma_f32_16x16x32_bf16 v[86:89], v[170:173], v[202:205], v[86:89]
	v_mfma_f32_16x16x32_bf16 v[82:85], v[178:181], v[202:205], v[82:85]
	v_mfma_f32_16x16x32_bf16 v[70:73], v[170:173], v[210:213], v[70:73]
	v_mfma_f32_16x16x32_bf16 v[66:69], v[178:181], v[210:213], v[66:69]
	s_nop 0
	s_barrier
	s_add_i32 s30, s51, s36
	v_lshl_add_u64 v[214:215], v[214:215], 0, s[8:9]
	s_mov_b32 m0, s30
	ds_read_b128 v[182:185], v147 offset:49152
	ds_read_b128 v[186:189], v147 offset:50176
	ds_read_b128 v[190:193], v147 offset:51200
	ds_read_b128 v[194:197], v147 offset:52224
	ds_read_b128 v[198:201], v147 offset:53248
	ds_read_b128 v[202:205], v147 offset:54272
	ds_read_b128 v[206:209], v147 offset:55296
	ds_read_b128 v[210:213], v147 offset:56320
	global_load_lds_dwordx4 v[214:215], off
	s_add_i32 m0, s30, 0x2000
	s_add_u32 s28, s28, 0x80080
	v_lshl_add_u64 v[214:215], v[216:217], 0, s[8:9]
	s_addc_u32 s29, s29, 0
	s_add_i32 s30, s52, s36
	global_load_lds_dwordx4 v[214:215], off
	v_lshl_add_u64 v[214:215], s[28:29], 0, v[132:133]
	s_mov_b32 m0, s30
	s_nop 0
	global_load_lds_dwordx4 v[214:215], off
	v_lshl_add_u64 v[214:215], s[28:29], 0, v[136:137]
	s_add_i32 m0, s30, 0x2000
	s_nop 0
	global_load_lds_dwordx4 v[214:215], off
	v_lshl_add_u64 v[214:215], v[218:219], 0, s[8:9]
	s_mov_b32 m0, s44
	s_nop 0
	global_load_lds_dwordx4 v[214:215], off
	v_lshl_add_u64 v[214:215], v[220:221], 0, s[8:9]
	s_mov_b32 m0, s45
	s_nop 0
	global_load_lds_dwordx4 v[214:215], off
	s_waitcnt vmcnt(8)
	s_waitcnt lgkmcnt(0)
	s_barrier
	s_nop 0
	s_waitcnt lgkmcnt(0)
	v_mfma_f32_16x16x32_bf16 v[62:65], v[148:151], v[182:185], v[62:65]
	v_mfma_f32_16x16x32_bf16 v[58:61], v[156:159], v[182:185], v[58:61]
	v_mfma_f32_16x16x32_bf16 v[46:49], v[148:151], v[190:193], v[46:49]
	v_mfma_f32_16x16x32_bf16 v[42:45], v[156:159], v[190:193], v[42:45]
	v_mfma_f32_16x16x32_bf16 v[30:33], v[148:151], v[198:201], v[30:33]
	v_mfma_f32_16x16x32_bf16 v[26:29], v[156:159], v[198:201], v[26:29]
	v_mfma_f32_16x16x32_bf16 v[14:17], v[148:151], v[206:209], v[14:17]
	v_mfma_f32_16x16x32_bf16 v[10:13], v[156:159], v[206:209], v[10:13]
	v_mfma_f32_16x16x32_bf16 v[62:65], v[152:155], v[186:189], v[62:65]
	v_mfma_f32_16x16x32_bf16 v[58:61], v[160:163], v[186:189], v[58:61]
	v_mfma_f32_16x16x32_bf16 v[46:49], v[152:155], v[194:197], v[46:49]
	v_mfma_f32_16x16x32_bf16 v[42:45], v[160:163], v[194:197], v[42:45]
	v_mfma_f32_16x16x32_bf16 v[30:33], v[152:155], v[202:205], v[30:33]
	v_mfma_f32_16x16x32_bf16 v[26:29], v[160:163], v[202:205], v[26:29]
	v_mfma_f32_16x16x32_bf16 v[14:17], v[152:155], v[210:213], v[14:17]
	v_mfma_f32_16x16x32_bf16 v[10:13], v[160:163], v[210:213], v[10:13]
	s_nop 0
	s_nop 0
	v_mfma_f32_16x16x32_bf16 v[54:57], v[166:169], v[182:185], v[54:57]
	v_mfma_f32_16x16x32_bf16 v[50:53], v[174:177], v[182:185], v[50:53]
	v_mfma_f32_16x16x32_bf16 v[38:41], v[166:169], v[190:193], v[38:41]
	v_mfma_f32_16x16x32_bf16 v[34:37], v[174:177], v[190:193], v[34:37]
	v_mfma_f32_16x16x32_bf16 v[22:25], v[166:169], v[198:201], v[22:25]
	v_mfma_f32_16x16x32_bf16 v[18:21], v[174:177], v[198:201], v[18:21]
	v_mfma_f32_16x16x32_bf16 v[6:9], v[166:169], v[206:209], v[6:9]
	v_mfma_f32_16x16x32_bf16 v[2:5], v[174:177], v[206:209], v[2:5]
	v_mfma_f32_16x16x32_bf16 v[54:57], v[170:173], v[186:189], v[54:57]
	v_mfma_f32_16x16x32_bf16 v[50:53], v[178:181], v[186:189], v[50:53]
	v_mfma_f32_16x16x32_bf16 v[38:41], v[170:173], v[194:197], v[38:41]
	v_mfma_f32_16x16x32_bf16 v[34:37], v[178:181], v[194:197], v[34:37]
	v_mfma_f32_16x16x32_bf16 v[22:25], v[170:173], v[202:205], v[22:25]
	v_mfma_f32_16x16x32_bf16 v[18:21], v[178:181], v[202:205], v[18:21]
	v_mfma_f32_16x16x32_bf16 v[6:9], v[170:173], v[210:213], v[6:9]
	v_mfma_f32_16x16x32_bf16 v[2:5], v[178:181], v[210:213], v[2:5]
	s_nop 0
	s_add_i32 s50, s50, 2
	s_add_u32 s26, s26, 0x100
	s_addc_u32 s27, s27, 0
	s_add_u32 s25, s25, 0x100
	s_addc_u32 s33, s33, 0
	s_cmp_gt_u32 s50, 29
	s_barrier
	s_cbranch_scc0 .LBB0_277
	s_setprio 0
	s_and_b64 vcc, exec, s[10:11]
	s_cbranch_vccz .LBB0_280
	s_barrier

.Lsp_p4:
.LBB0_704:
	ds_read_b128 v[144:147], v152
	ds_read_b128 v[156:159], v152 offset:1024
	ds_read_b128 v[160:163], v152 offset:2048
	ds_read_b128 v[166:169], v152 offset:3072
	ds_read_b128 v[170:173], v153
	ds_read_b128 v[174:177], v153 offset:1024
	ds_read_b128 v[178:181], v153 offset:2048
	ds_read_b128 v[182:185], v153 offset:3072
	s_add_u32 s24, s22, 0xfff80080
	s_addc_u32 s25, s23, -1
	s_cmp_eq_u32 s45, 28
	s_cselect_b32 s27, s17, s25
	s_cselect_b32 s26, s16, s24
	s_cselect_b32 s25, s21, s15
	s_cselect_b32 s24, s20, s5
	s_mov_b32 m0, s42
	v_lshl_add_u64 v[218:219], s[22:23], 0, v[140:141]
	ds_read_b128 v[186:189], v154
	ds_read_b128 v[190:193], v154 offset:1024
	ds_read_b128 v[194:197], v154 offset:2048
	ds_read_b128 v[198:201], v154 offset:3072
	ds_read_b128 v[202:205], v154 offset:4096
	ds_read_b128 v[206:209], v154 offset:5120
	ds_read_b128 v[210:213], v154 offset:6144
	ds_read_b128 v[214:217], v154 offset:7168
	global_load_lds_dwordx4 v[218:219], off
	v_lshl_add_u64 v[218:219], s[22:23], 0, v[142:143]
	s_add_i32 m0, s30, 0xe000
	s_nop 0
	global_load_lds_dwordx4 v[218:219], off
	s_waitcnt vmcnt(8)
	s_waitcnt lgkmcnt(0)
	s_barrier
	s_nop 0
	s_waitcnt lgkmcnt(0)
	v_mfma_f32_16x16x32_bf16 v[126:129], v[144:147], v[186:189], v[126:129]
	v_mfma_f32_16x16x32_bf16 v[122:125], v[160:163], v[186:189], v[122:125]
	v_mfma_f32_16x16x32_bf16 v[110:113], v[144:147], v[194:197], v[110:113]
	v_mfma_f32_16x16x32_bf16 v[106:109], v[160:163], v[194:197], v[106:109]
	v_mfma_f32_16x16x32_bf16 v[94:97], v[144:147], v[202:205], v[94:97]
	v_mfma_f32_16x16x32_bf16 v[90:93], v[160:163], v[202:205], v[90:93]
	v_mfma_f32_16x16x32_bf16 v[78:81], v[144:147], v[210:213], v[78:81]
	v_mfma_f32_16x16x32_bf16 v[74:77], v[160:163], v[210:213], v[74:77]
	v_mfma_f32_16x16x32_bf16 v[126:129], v[156:159], v[190:193], v[126:129]
	v_mfma_f32_16x16x32_bf16 v[122:125], v[166:169], v[190:193], v[122:125]
	v_mfma_f32_16x16x32_bf16 v[110:113], v[156:159], v[198:201], v[110:113]
	v_mfma_f32_16x16x32_bf16 v[106:109], v[166:169], v[198:201], v[106:109]
	v_mfma_f32_16x16x32_bf16 v[94:97], v[156:159], v[206:209], v[94:97]
	v_mfma_f32_16x16x32_bf16 v[90:93], v[166:169], v[206:209], v[90:93]
	v_mfma_f32_16x16x32_bf16 v[78:81], v[156:159], v[214:217], v[78:81]
	v_mfma_f32_16x16x32_bf16 v[74:77], v[166:169], v[214:217], v[74:77]
	s_nop 0
	s_nop 0
	v_mfma_f32_16x16x32_bf16 v[118:121], v[170:173], v[186:189], v[118:121]
	v_mfma_f32_16x16x32_bf16 v[114:117], v[178:181], v[186:189], v[114:117]
	v_mfma_f32_16x16x32_bf16 v[102:105], v[170:173], v[194:197], v[102:105]
	v_mfma_f32_16x16x32_bf16 v[98:101], v[178:181], v[194:197], v[98:101]
	v_mfma_f32_16x16x32_bf16 v[86:89], v[170:173], v[202:205], v[86:89]
	v_mfma_f32_16x16x32_bf16 v[82:85], v[178:181], v[202:205], v[82:85]
	v_mfma_f32_16x16x32_bf16 v[70:73], v[170:173], v[210:213], v[70:73]
	v_mfma_f32_16x16x32_bf16 v[66:69], v[178:181], v[210:213], v[66:69]
	v_mfma_f32_16x16x32_bf16 v[118:121], v[174:177], v[190:193], v[118:121]
	v_mfma_f32_16x16x32_bf16 v[114:117], v[182:185], v[190:193], v[114:117]
	v_mfma_f32_16x16x32_bf16 v[102:105], v[174:177], v[198:201], v[102:105]
	v_mfma_f32_16x16x32_bf16 v[98:101], v[182:185], v[198:201], v[98:101]
	v_mfma_f32_16x16x32_bf16 v[86:89], v[174:177], v[206:209], v[86:89]
	v_mfma_f32_16x16x32_bf16 v[82:85], v[182:185], v[206:209], v[82:85]
	v_mfma_f32_16x16x32_bf16 v[70:73], v[174:177], v[214:217], v[70:73]
	v_mfma_f32_16x16x32_bf16 v[66:69], v[182:185], v[214:217], v[66:69]
	s_nop 0
	s_barrier
	s_add_i32 s46, s40, s29
	v_lshl_add_u64 v[218:219], s[24:25], 0, v[134:135]
	s_mov_b32 m0, s46
	ds_read_b128 v[186:189], v154 offset:16384
	ds_read_b128 v[190:193], v154 offset:17408
	ds_read_b128 v[194:197], v154 offset:18432
	ds_read_b128 v[198:201], v154 offset:19456
	ds_read_b128 v[202:205], v154 offset:20480
	ds_read_b128 v[206:209], v154 offset:21504
	ds_read_b128 v[210:213], v154 offset:22528
	ds_read_b128 v[214:217], v154 offset:23552
	global_load_lds_dwordx4 v[218:219], off
	s_add_i32 m0, s46, 0x2000
	s_add_u32 s46, s24, 0x80000
	v_lshl_add_u64 v[220:221], s[24:25], 0, v[138:139]
	s_addc_u32 s47, s25, 0
	s_add_i32 s48, s41, s29
	global_load_lds_dwordx4 v[220:221], off
	v_lshl_add_u64 v[222:223], s[46:47], 0, v[134:135]
	s_mov_b32 m0, s48
	v_lshl_add_u64 v[224:225], s[26:27], 0, v[136:137]
	global_load_lds_dwordx4 v[222:223], off
	v_lshl_add_u64 v[222:223], s[46:47], 0, v[138:139]
	s_add_i32 m0, s48, 0x2000
	s_nop 0
	global_load_lds_dwordx4 v[222:223], off
	v_lshl_add_u64 v[222:223], s[26:27], 0, v[132:133]
	s_mov_b32 m0, s30
	s_nop 0
	global_load_lds_dwordx4 v[222:223], off
	s_mov_b32 m0, s31
	s_nop 0
	global_load_lds_dwordx4 v[224:225], off
	s_waitcnt vmcnt(8)
	s_waitcnt lgkmcnt(0)
	s_barrier
	s_nop 0
	s_waitcnt lgkmcnt(0)
	v_mfma_f32_16x16x32_bf16 v[62:65], v[144:147], v[186:189], v[62:65]
	v_mfma_f32_16x16x32_bf16 v[58:61], v[160:163], v[186:189], v[58:61]
	v_mfma_f32_16x16x32_bf16 v[46:49], v[144:147], v[194:197], v[46:49]
	v_mfma_f32_16x16x32_bf16 v[42:45], v[160:163], v[194:197], v[42:45]
	v_mfma_f32_16x16x32_bf16 v[30:33], v[144:147], v[202:205], v[30:33]
	v_mfma_f32_16x16x32_bf16 v[26:29], v[160:163], v[202:205], v[26:29]
	v_mfma_f32_16x16x32_bf16 v[14:17], v[144:147], v[210:213], v[14:17]
	v_mfma_f32_16x16x32_bf16 v[10:13], v[160:163], v[210:213], v[10:13]
	v_mfma_f32_16x16x32_bf16 v[62:65], v[156:159], v[190:193], v[62:65]
	v_mfma_f32_16x16x32_bf16 v[58:61], v[166:169], v[190:193], v[58:61]
	v_mfma_f32_16x16x32_bf16 v[46:49], v[156:159], v[198:201], v[46:49]
	v_mfma_f32_16x16x32_bf16 v[42:45], v[166:169], v[198:201], v[42:45]
	v_mfma_f32_16x16x32_bf16 v[30:33], v[156:159], v[206:209], v[30:33]
	v_mfma_f32_16x16x32_bf16 v[26:29], v[166:169], v[206:209], v[26:29]
	v_mfma_f32_16x16x32_bf16 v[14:17], v[156:159], v[214:217], v[14:17]
	v_mfma_f32_16x16x32_bf16 v[10:13], v[166:169], v[214:217], v[10:13]
	s_nop 0
	s_nop 0
	v_mfma_f32_16x16x32_bf16 v[54:57], v[170:173], v[186:189], v[54:57]
	v_mfma_f32_16x16x32_bf16 v[50:53], v[178:181], v[186:189], v[50:53]
	v_mfma_f32_16x16x32_bf16 v[38:41], v[170:173], v[194:197], v[38:41]
	v_mfma_f32_16x16x32_bf16 v[34:37], v[178:181], v[194:197], v[34:37]
	v_mfma_f32_16x16x32_bf16 v[22:25], v[170:173], v[202:205], v[22:25]
	v_mfma_f32_16x16x32_bf16 v[18:21], v[178:181], v[202:205], v[18:21]
	v_mfma_f32_16x16x32_bf16 v[6:9], v[170:173], v[210:213], v[6:9]
	v_mfma_f32_16x16x32_bf16 v[2:5], v[178:181], v[210:213], v[2:5]
	v_mfma_f32_16x16x32_bf16 v[54:57], v[174:177], v[190:193], v[54:57]
	v_mfma_f32_16x16x32_bf16 v[50:53], v[182:185], v[190:193], v[50:53]
	v_mfma_f32_16x16x32_bf16 v[38:41], v[174:177], v[198:201], v[38:41]
	v_mfma_f32_16x16x32_bf16 v[34:37], v[182:185], v[198:201], v[34:37]
	v_mfma_f32_16x16x32_bf16 v[22:25], v[174:177], v[206:209], v[22:25]
	v_mfma_f32_16x16x32_bf16 v[18:21], v[182:185], v[206:209], v[18:21]
	v_mfma_f32_16x16x32_bf16 v[6:9], v[174:177], v[214:217], v[6:9]
	v_mfma_f32_16x16x32_bf16 v[2:5], v[182:185], v[214:217], v[2:5]
	s_nop 0
	s_barrier
	s_add_i32 s46, 0, 0x18000
	v_add_u32_e32 v155, s46, v1
	s_add_i32 s47, 0, 0x1c000
	ds_read_b128 v[144:147], v155
	ds_read_b128 v[156:159], v155 offset:1024
	ds_read_b128 v[160:163], v155 offset:2048
	ds_read_b128 v[166:169], v155 offset:3072
	v_add_u32_e32 v155, s47, v1
	ds_read_b128 v[170:173], v155
	ds_read_b128 v[174:177], v155 offset:1024
	ds_read_b128 v[178:181], v155 offset:2048
	ds_read_b128 v[182:185], v155 offset:3072
	s_add_u32 s26, s26, 0x80000
	s_addc_u32 s27, s27, 0
	s_mov_b32 m0, s33
	v_lshl_add_u64 v[226:227], s[26:27], 0, v[132:133]
	ds_read_b128 v[186:189], v154 offset:32768
	ds_read_b128 v[190:193], v154 offset:33792
	ds_read_b128 v[194:197], v154 offset:34816
	ds_read_b128 v[198:201], v154 offset:35840
	ds_read_b128 v[202:205], v154 offset:36864
	ds_read_b128 v[206:209], v154 offset:37888
	ds_read_b128 v[210:213], v154 offset:38912
	ds_read_b128 v[214:217], v154 offset:39936
	global_load_lds_dwordx4 v[226:227], off
	v_lshl_add_u64 v[226:227], s[26:27], 0, v[136:137]
	s_mov_b32 m0, s34
	s_nop 0
	global_load_lds_dwordx4 v[226:227], off
	s_waitcnt vmcnt(8)
	s_waitcnt lgkmcnt(0)
	s_barrier
	s_nop 0
	s_waitcnt lgkmcnt(0)
	v_mfma_f32_16x16x32_bf16 v[126:129], v[144:147], v[186:189], v[126:129]
	v_mfma_f32_16x16x32_bf16 v[122:125], v[160:163], v[186:189], v[122:125]
	v_mfma_f32_16x16x32_bf16 v[110:113], v[144:147], v[194:197], v[110:113]
	v_mfma_f32_16x16x32_bf16 v[106:109], v[160:163], v[194:197], v[106:109]
	v_mfma_f32_16x16x32_bf16 v[94:97], v[144:147], v[202:205], v[94:97]
	v_mfma_f32_16x16x32_bf16 v[90:93], v[160:163], v[202:205], v[90:93]
	v_mfma_f32_16x16x32_bf16 v[78:81], v[144:147], v[210:213], v[78:81]
	v_mfma_f32_16x16x32_bf16 v[74:77], v[160:163], v[210:213], v[74:77]
	v_mfma_f32_16x16x32_bf16 v[126:129], v[156:159], v[190:193], v[126:129]
	v_mfma_f32_16x16x32_bf16 v[122:125], v[166:169], v[190:193], v[122:125]
	v_mfma_f32_16x16x32_bf16 v[110:113], v[156:159], v[198:201], v[110:113]
	v_mfma_f32_16x16x32_bf16 v[106:109], v[166:169], v[198:201], v[106:109]
	v_mfma_f32_16x16x32_bf16 v[94:97], v[156:159], v[206:209], v[94:97]
	v_mfma_f32_16x16x32_bf16 v[90:93], v[166:169], v[206:209], v[90:93]
	v_mfma_f32_16x16x32_bf16 v[78:81], v[156:159], v[214:217], v[78:81]
	v_mfma_f32_16x16x32_bf16 v[74:77], v[166:169], v[214:217], v[74:77]
	s_nop 0
	s_nop 0
	v_mfma_f32_16x16x32_bf16 v[118:121], v[170:173], v[186:189], v[118:121]
	v_mfma_f32_16x16x32_bf16 v[114:117], v[178:181], v[186:189], v[114:117]
	v_mfma_f32_16x16x32_bf16 v[102:105], v[170:173], v[194:197], v[102:105]
	v_mfma_f32_16x16x32_bf16 v[98:101], v[178:181], v[194:197], v[98:101]
	v_mfma_f32_16x16x32_bf16 v[86:89], v[170:173], v[202:205], v[86:89]
	v_mfma_f32_16x16x32_bf16 v[82:85], v[178:181], v[202:205], v[82:85]
	v_mfma_f32_16x16x32_bf16 v[70:73], v[170:173], v[210:213], v[70:73]
	v_mfma_f32_16x16x32_bf16 v[66:69], v[178:181], v[210:213], v[66:69]
	v_mfma_f32_16x16x32_bf16 v[118:121], v[174:177], v[190:193], v[118:121]
	v_mfma_f32_16x16x32_bf16 v[114:117], v[182:185], v[190:193], v[114:117]
	v_mfma_f32_16x16x32_bf16 v[102:105], v[174:177], v[198:201], v[102:105]
	v_mfma_f32_16x16x32_bf16 v[98:101], v[182:185], v[198:201], v[98:101]
	v_mfma_f32_16x16x32_bf16 v[86:89], v[174:177], v[206:209], v[86:89]
	v_mfma_f32_16x16x32_bf16 v[82:85], v[182:185], v[206:209], v[82:85]
	v_mfma_f32_16x16x32_bf16 v[70:73], v[174:177], v[214:217], v[70:73]
	v_mfma_f32_16x16x32_bf16 v[66:69], v[182:185], v[214:217], v[66:69]
	s_nop 0
	s_barrier
	s_add_i32 s26, s46, s29
	v_lshl_add_u64 v[218:219], v[218:219], 0, s[10:11]
	s_mov_b32 m0, s26
	ds_read_b128 v[186:189], v154 offset:49152
	ds_read_b128 v[190:193], v154 offset:50176
	ds_read_b128 v[194:197], v154 offset:51200
	ds_read_b128 v[198:201], v154 offset:52224
	ds_read_b128 v[202:205], v154 offset:53248
	ds_read_b128 v[206:209], v154 offset:54272
	ds_read_b128 v[210:213], v154 offset:55296
	ds_read_b128 v[214:217], v154 offset:56320
	global_load_lds_dwordx4 v[218:219], off
	s_add_i32 m0, s26, 0x2000
	s_add_u32 s24, s24, 0x80080
	v_lshl_add_u64 v[218:219], v[220:221], 0, s[10:11]
	s_addc_u32 s25, s25, 0
	s_add_i32 s26, s47, s29
	global_load_lds_dwordx4 v[218:219], off
	v_lshl_add_u64 v[218:219], s[24:25], 0, v[134:135]
	s_mov_b32 m0, s26
	s_nop 0
	global_load_lds_dwordx4 v[218:219], off
	v_lshl_add_u64 v[218:219], s[24:25], 0, v[138:139]
	s_add_i32 m0, s26, 0x2000
	s_nop 0
	global_load_lds_dwordx4 v[218:219], off
	v_lshl_add_u64 v[218:219], v[222:223], 0, s[10:11]
	s_mov_b32 m0, s38
	s_nop 0
	global_load_lds_dwordx4 v[218:219], off
	v_lshl_add_u64 v[218:219], v[224:225], 0, s[10:11]
	s_mov_b32 m0, s39
	s_nop 0
	global_load_lds_dwordx4 v[218:219], off
	s_waitcnt vmcnt(8)
	s_waitcnt lgkmcnt(0)
	s_barrier
	s_nop 0
	s_waitcnt lgkmcnt(0)
	v_mfma_f32_16x16x32_bf16 v[62:65], v[144:147], v[186:189], v[62:65]
	v_mfma_f32_16x16x32_bf16 v[58:61], v[160:163], v[186:189], v[58:61]
	v_mfma_f32_16x16x32_bf16 v[46:49], v[144:147], v[194:197], v[46:49]
	v_mfma_f32_16x16x32_bf16 v[42:45], v[160:163], v[194:197], v[42:45]
	v_mfma_f32_16x16x32_bf16 v[30:33], v[144:147], v[202:205], v[30:33]
	v_mfma_f32_16x16x32_bf16 v[26:29], v[160:163], v[202:205], v[26:29]
	v_mfma_f32_16x16x32_bf16 v[14:17], v[144:147], v[210:213], v[14:17]
	v_mfma_f32_16x16x32_bf16 v[10:13], v[160:163], v[210:213], v[10:13]
	v_mfma_f32_16x16x32_bf16 v[62:65], v[156:159], v[190:193], v[62:65]
	v_mfma_f32_16x16x32_bf16 v[58:61], v[166:169], v[190:193], v[58:61]
	v_mfma_f32_16x16x32_bf16 v[46:49], v[156:159], v[198:201], v[46:49]
	v_mfma_f32_16x16x32_bf16 v[42:45], v[166:169], v[198:201], v[42:45]
	v_mfma_f32_16x16x32_bf16 v[30:33], v[156:159], v[206:209], v[30:33]
	v_mfma_f32_16x16x32_bf16 v[26:29], v[166:169], v[206:209], v[26:29]
	v_mfma_f32_16x16x32_bf16 v[14:17], v[156:159], v[214:217], v[14:17]
	v_mfma_f32_16x16x32_bf16 v[10:13], v[166:169], v[214:217], v[10:13]
	s_nop 0
	s_nop 0
	v_mfma_f32_16x16x32_bf16 v[54:57], v[170:173], v[186:189], v[54:57]
	v_mfma_f32_16x16x32_bf16 v[50:53], v[178:181], v[186:189], v[50:53]
	v_mfma_f32_16x16x32_bf16 v[38:41], v[170:173], v[194:197], v[38:41]
	v_mfma_f32_16x16x32_bf16 v[34:37], v[178:181], v[194:197], v[34:37]
	v_mfma_f32_16x16x32_bf16 v[22:25], v[170:173], v[202:205], v[22:25]
	v_mfma_f32_16x16x32_bf16 v[18:21], v[178:181], v[202:205], v[18:21]
	v_mfma_f32_16x16x32_bf16 v[6:9], v[170:173], v[210:213], v[6:9]
	v_mfma_f32_16x16x32_bf16 v[2:5], v[178:181], v[210:213], v[2:5]
	v_mfma_f32_16x16x32_bf16 v[54:57], v[174:177], v[190:193], v[54:57]
	v_mfma_f32_16x16x32_bf16 v[50:53], v[182:185], v[190:193], v[50:53]
	v_mfma_f32_16x16x32_bf16 v[38:41], v[174:177], v[198:201], v[38:41]
	v_mfma_f32_16x16x32_bf16 v[34:37], v[182:185], v[198:201], v[34:37]
	v_mfma_f32_16x16x32_bf16 v[22:25], v[174:177], v[206:209], v[22:25]
	v_mfma_f32_16x16x32_bf16 v[18:21], v[182:185], v[206:209], v[18:21]
	v_mfma_f32_16x16x32_bf16 v[6:9], v[174:177], v[214:217], v[6:9]
	v_mfma_f32_16x16x32_bf16 v[2:5], v[182:185], v[214:217], v[2:5]
	s_nop 0
	s_add_i32 s45, s45, 2
	s_add_u32 s22, s22, 0x100
	s_addc_u32 s23, s23, 0
	s_add_u32 s5, s5, 0x100
	s_addc_u32 s15, s15, 0
	s_cmp_gt_u32 s45, 29
	s_barrier
	s_cbranch_scc0 .LBB0_704
	s_setprio 0
	s_and_b64 vcc, exec, s[12:13]
	s_cbranch_vccz .LBB0_707
	s_barrier

.Lsp_p5:
.LBB0_842:
	v_add_u32_e32 v158, s36, v152
	v_add_u32_e32 v162, s37, v152
	ds_read_b128 v[142:145], v158
	ds_read_b128 v[146:149], v158 offset:1024
	ds_read_b128 v[154:157], v158 offset:2048
	ds_read_b128 v[158:161], v158 offset:3072
	ds_read_b128 v[166:169], v162
	ds_read_b128 v[170:173], v162 offset:1024
	ds_read_b128 v[174:177], v162 offset:2048
	ds_read_b128 v[178:181], v162 offset:3072
	s_add_i32 s49, s20, 2
	s_add_u32 s21, s4, 0xfffa0080
	s_addc_u32 s22, s5, -1
	s_cmp_eq_u32 s46, s20
	s_cselect_b32 s20, s16, s47
	s_cselect_b32 s23, s15, s22
	s_cselect_b32 s22, s14, s21
	s_cselect_b32 s21, s17, s48
	v_lshl_add_u64 v[162:163], s[4:5], 0, v[138:139]
	s_add_i32 m0, s26, 0xc000
	ds_read_b128 v[182:185], v153
	ds_read_b128 v[186:189], v153 offset:1024
	ds_read_b128 v[190:193], v153 offset:2048
	ds_read_b128 v[194:197], v153 offset:3072
	ds_read_b128 v[198:201], v153 offset:4096
	ds_read_b128 v[202:205], v153 offset:5120
	ds_read_b128 v[206:209], v153 offset:6144
	ds_read_b128 v[210:213], v153 offset:7168
	global_load_lds_dwordx4 v[162:163], off
	v_lshl_add_u64 v[162:163], s[4:5], 0, v[140:141]
	s_add_i32 m0, s26, 0xe000
	s_nop 0
	global_load_lds_dwordx4 v[162:163], off
	s_waitcnt vmcnt(8)
	s_waitcnt lgkmcnt(0)
	s_barrier
	s_nop 0
	s_waitcnt lgkmcnt(0)
	v_mfma_f32_16x16x32_bf16 v[126:129], v[142:145], v[182:185], v[126:129]
	v_mfma_f32_16x16x32_bf16 v[122:125], v[154:157], v[182:185], v[122:125]
	v_mfma_f32_16x16x32_bf16 v[118:121], v[142:145], v[190:193], v[118:121]
	v_mfma_f32_16x16x32_bf16 v[114:117], v[154:157], v[190:193], v[114:117]
	v_mfma_f32_16x16x32_bf16 v[110:113], v[142:145], v[198:201], v[110:113]
	v_mfma_f32_16x16x32_bf16 v[106:109], v[154:157], v[198:201], v[106:109]
	v_mfma_f32_16x16x32_bf16 v[102:105], v[142:145], v[206:209], v[102:105]
	v_mfma_f32_16x16x32_bf16 v[98:101], v[154:157], v[206:209], v[98:101]
	v_mfma_f32_16x16x32_bf16 v[126:129], v[146:149], v[186:189], v[126:129]
	v_mfma_f32_16x16x32_bf16 v[122:125], v[158:161], v[186:189], v[122:125]
	v_mfma_f32_16x16x32_bf16 v[118:121], v[146:149], v[194:197], v[118:121]
	v_mfma_f32_16x16x32_bf16 v[114:117], v[158:161], v[194:197], v[114:117]
	v_mfma_f32_16x16x32_bf16 v[110:113], v[146:149], v[202:205], v[110:113]
	v_mfma_f32_16x16x32_bf16 v[106:109], v[158:161], v[202:205], v[106:109]
	v_mfma_f32_16x16x32_bf16 v[102:105], v[146:149], v[210:213], v[102:105]
	v_mfma_f32_16x16x32_bf16 v[98:101], v[158:161], v[210:213], v[98:101]
	s_nop 0
	s_nop 0
	v_mfma_f32_16x16x32_bf16 v[94:97], v[166:169], v[182:185], v[94:97]
	v_mfma_f32_16x16x32_bf16 v[90:93], v[174:177], v[182:185], v[90:93]
	v_mfma_f32_16x16x32_bf16 v[86:89], v[166:169], v[190:193], v[86:89]
	v_mfma_f32_16x16x32_bf16 v[82:85], v[174:177], v[190:193], v[82:85]
	v_mfma_f32_16x16x32_bf16 v[78:81], v[166:169], v[198:201], v[78:81]
	v_mfma_f32_16x16x32_bf16 v[74:77], v[174:177], v[198:201], v[74:77]
	v_mfma_f32_16x16x32_bf16 v[70:73], v[166:169], v[206:209], v[70:73]
	v_mfma_f32_16x16x32_bf16 v[66:69], v[174:177], v[206:209], v[66:69]
	v_mfma_f32_16x16x32_bf16 v[94:97], v[170:173], v[186:189], v[94:97]
	v_mfma_f32_16x16x32_bf16 v[90:93], v[178:181], v[186:189], v[90:93]
	v_mfma_f32_16x16x32_bf16 v[86:89], v[170:173], v[194:197], v[86:89]
	v_mfma_f32_16x16x32_bf16 v[82:85], v[178:181], v[194:197], v[82:85]
	v_mfma_f32_16x16x32_bf16 v[78:81], v[170:173], v[202:205], v[78:81]
	v_mfma_f32_16x16x32_bf16 v[74:77], v[178:181], v[202:205], v[74:77]
	v_mfma_f32_16x16x32_bf16 v[70:73], v[170:173], v[210:213], v[70:73]
	v_mfma_f32_16x16x32_bf16 v[66:69], v[178:181], v[210:213], v[66:69]
	s_nop 0
	s_barrier
	s_add_i32 s50, s36, s25
	v_lshl_add_u64 v[162:163], s[20:21], 0, v[132:133]
	s_mov_b32 m0, s50
	ds_read_b128 v[182:185], v153 offset:16384
	ds_read_b128 v[186:189], v153 offset:17408
	ds_read_b128 v[190:193], v153 offset:18432
	ds_read_b128 v[194:197], v153 offset:19456
	ds_read_b128 v[198:201], v153 offset:20480
	ds_read_b128 v[202:205], v153 offset:21504
	ds_read_b128 v[206:209], v153 offset:22528
	ds_read_b128 v[210:213], v153 offset:23552
	global_load_lds_dwordx4 v[162:163], off
	s_add_i32 m0, s50, 0x2000
	s_add_u32 s50, s20, 0x60000
	v_lshl_add_u64 v[214:215], s[20:21], 0, v[136:137]
	s_addc_u32 s51, s21, 0
	s_add_i32 s52, s37, s25
	global_load_lds_dwordx4 v[214:215], off
	v_lshl_add_u64 v[216:217], s[50:51], 0, v[132:133]
	s_mov_b32 m0, s52
	v_lshl_add_u64 v[218:219], s[22:23], 0, v[134:135]
	global_load_lds_dwordx4 v[216:217], off
	v_lshl_add_u64 v[216:217], s[50:51], 0, v[136:137]
	s_add_i32 m0, s52, 0x2000
	s_nop 0
	global_load_lds_dwordx4 v[216:217], off
	v_lshl_add_u64 v[216:217], s[22:23], 0, v[130:131]
	s_mov_b32 m0, s26
	s_nop 0
	global_load_lds_dwordx4 v[216:217], off
	s_mov_b32 m0, s27
	s_nop 0
	global_load_lds_dwordx4 v[218:219], off
	s_waitcnt vmcnt(8)
	s_waitcnt lgkmcnt(0)
	s_barrier
	s_nop 0
	s_waitcnt lgkmcnt(0)
	v_mfma_f32_16x16x32_bf16 v[62:65], v[142:145], v[182:185], v[62:65]
	v_mfma_f32_16x16x32_bf16 v[58:61], v[154:157], v[182:185], v[58:61]
	v_mfma_f32_16x16x32_bf16 v[54:57], v[142:145], v[190:193], v[54:57]
	v_mfma_f32_16x16x32_bf16 v[50:53], v[154:157], v[190:193], v[50:53]
	v_mfma_f32_16x16x32_bf16 v[46:49], v[142:145], v[198:201], v[46:49]
	v_mfma_f32_16x16x32_bf16 v[42:45], v[154:157], v[198:201], v[42:45]
	v_mfma_f32_16x16x32_bf16 v[38:41], v[142:145], v[206:209], v[38:41]
	v_mfma_f32_16x16x32_bf16 v[34:37], v[154:157], v[206:209], v[34:37]
	v_mfma_f32_16x16x32_bf16 v[62:65], v[146:149], v[186:189], v[62:65]
	v_mfma_f32_16x16x32_bf16 v[58:61], v[158:161], v[186:189], v[58:61]
	v_mfma_f32_16x16x32_bf16 v[54:57], v[146:149], v[194:197], v[54:57]
	v_mfma_f32_16x16x32_bf16 v[50:53], v[158:161], v[194:197], v[50:53]
	v_mfma_f32_16x16x32_bf16 v[46:49], v[146:149], v[202:205], v[46:49]
	v_mfma_f32_16x16x32_bf16 v[42:45], v[158:161], v[202:205], v[42:45]
	v_mfma_f32_16x16x32_bf16 v[38:41], v[146:149], v[210:213], v[38:41]
	v_mfma_f32_16x16x32_bf16 v[34:37], v[158:161], v[210:213], v[34:37]
	s_nop 0
	s_nop 0
	v_mfma_f32_16x16x32_bf16 v[30:33], v[166:169], v[182:185], v[30:33]
	v_mfma_f32_16x16x32_bf16 v[26:29], v[174:177], v[182:185], v[26:29]
	v_mfma_f32_16x16x32_bf16 v[22:25], v[166:169], v[190:193], v[22:25]
	v_mfma_f32_16x16x32_bf16 v[18:21], v[174:177], v[190:193], v[18:21]
	v_mfma_f32_16x16x32_bf16 v[14:17], v[166:169], v[198:201], v[14:17]
	v_mfma_f32_16x16x32_bf16 v[10:13], v[174:177], v[198:201], v[10:13]
	v_mfma_f32_16x16x32_bf16 v[6:9], v[166:169], v[206:209], v[6:9]
	v_mfma_f32_16x16x32_bf16 v[2:5], v[174:177], v[206:209], v[2:5]
	v_mfma_f32_16x16x32_bf16 v[30:33], v[170:173], v[186:189], v[30:33]
	v_mfma_f32_16x16x32_bf16 v[26:29], v[178:181], v[186:189], v[26:29]
	v_mfma_f32_16x16x32_bf16 v[22:25], v[170:173], v[194:197], v[22:25]
	v_mfma_f32_16x16x32_bf16 v[18:21], v[178:181], v[194:197], v[18:21]
	v_mfma_f32_16x16x32_bf16 v[14:17], v[170:173], v[202:205], v[14:17]
	v_mfma_f32_16x16x32_bf16 v[10:13], v[178:181], v[202:205], v[10:13]
	v_mfma_f32_16x16x32_bf16 v[6:9], v[170:173], v[210:213], v[6:9]
	v_mfma_f32_16x16x32_bf16 v[2:5], v[178:181], v[210:213], v[2:5]
	s_nop 0
	s_barrier
	s_add_i32 s50, 0, 0x18000
	s_add_i32 s51, 0, 0x1c000
	v_add_u32_e32 v158, s50, v152
	v_add_u32_e32 v164, s51, v152
	ds_read_b128 v[142:145], v158
	ds_read_b128 v[146:149], v158 offset:1024
	ds_read_b128 v[154:157], v158 offset:2048
	ds_read_b128 v[158:161], v158 offset:3072
	ds_read_b128 v[166:169], v164
	ds_read_b128 v[170:173], v164 offset:1024
	ds_read_b128 v[174:177], v164 offset:2048
	ds_read_b128 v[178:181], v164 offset:3072
	s_add_u32 s22, s22, 0x60000
	s_addc_u32 s23, s23, 0
	s_mov_b32 m0, s28
	v_lshl_add_u64 v[220:221], s[22:23], 0, v[130:131]
	ds_read_b128 v[182:185], v153 offset:32768
	ds_read_b128 v[186:189], v153 offset:33792
	ds_read_b128 v[190:193], v153 offset:34816
	ds_read_b128 v[194:197], v153 offset:35840
	ds_read_b128 v[198:201], v153 offset:36864
	ds_read_b128 v[202:205], v153 offset:37888
	ds_read_b128 v[206:209], v153 offset:38912
	ds_read_b128 v[210:213], v153 offset:39936
	global_load_lds_dwordx4 v[220:221], off
	v_lshl_add_u64 v[220:221], s[22:23], 0, v[134:135]
	s_mov_b32 m0, s29
	s_nop 0
	global_load_lds_dwordx4 v[220:221], off
	s_waitcnt vmcnt(8)
	s_waitcnt lgkmcnt(0)
	s_barrier
	s_nop 0
	s_waitcnt lgkmcnt(0)
	v_mfma_f32_16x16x32_bf16 v[126:129], v[142:145], v[182:185], v[126:129]
	v_mfma_f32_16x16x32_bf16 v[122:125], v[154:157], v[182:185], v[122:125]
	v_mfma_f32_16x16x32_bf16 v[118:121], v[142:145], v[190:193], v[118:121]
	v_mfma_f32_16x16x32_bf16 v[114:117], v[154:157], v[190:193], v[114:117]
	v_mfma_f32_16x16x32_bf16 v[110:113], v[142:145], v[198:201], v[110:113]
	v_mfma_f32_16x16x32_bf16 v[106:109], v[154:157], v[198:201], v[106:109]
	v_mfma_f32_16x16x32_bf16 v[102:105], v[142:145], v[206:209], v[102:105]
	v_mfma_f32_16x16x32_bf16 v[98:101], v[154:157], v[206:209], v[98:101]
	v_mfma_f32_16x16x32_bf16 v[126:129], v[146:149], v[186:189], v[126:129]
	v_mfma_f32_16x16x32_bf16 v[122:125], v[158:161], v[186:189], v[122:125]
	v_mfma_f32_16x16x32_bf16 v[118:121], v[146:149], v[194:197], v[118:121]
	v_mfma_f32_16x16x32_bf16 v[114:117], v[158:161], v[194:197], v[114:117]
	v_mfma_f32_16x16x32_bf16 v[110:113], v[146:149], v[202:205], v[110:113]
	v_mfma_f32_16x16x32_bf16 v[106:109], v[158:161], v[202:205], v[106:109]
	v_mfma_f32_16x16x32_bf16 v[102:105], v[146:149], v[210:213], v[102:105]
	v_mfma_f32_16x16x32_bf16 v[98:101], v[158:161], v[210:213], v[98:101]
	s_nop 0
	s_nop 0
	v_mfma_f32_16x16x32_bf16 v[94:97], v[166:169], v[182:185], v[94:97]
	v_mfma_f32_16x16x32_bf16 v[90:93], v[174:177], v[182:185], v[90:93]
	v_mfma_f32_16x16x32_bf16 v[86:89], v[166:169], v[190:193], v[86:89]
	v_mfma_f32_16x16x32_bf16 v[82:85], v[174:177], v[190:193], v[82:85]
	v_mfma_f32_16x16x32_bf16 v[78:81], v[166:169], v[198:201], v[78:81]
	v_mfma_f32_16x16x32_bf16 v[74:77], v[174:177], v[198:201], v[74:77]
	v_mfma_f32_16x16x32_bf16 v[70:73], v[166:169], v[206:209], v[70:73]
	v_mfma_f32_16x16x32_bf16 v[66:69], v[174:177], v[206:209], v[66:69]
	v_mfma_f32_16x16x32_bf16 v[94:97], v[170:173], v[186:189], v[94:97]
	v_mfma_f32_16x16x32_bf16 v[90:93], v[178:181], v[186:189], v[90:93]
	v_mfma_f32_16x16x32_bf16 v[86:89], v[170:173], v[194:197], v[86:89]
	v_mfma_f32_16x16x32_bf16 v[82:85], v[178:181], v[194:197], v[82:85]
	v_mfma_f32_16x16x32_bf16 v[78:81], v[170:173], v[202:205], v[78:81]
	v_mfma_f32_16x16x32_bf16 v[74:77], v[178:181], v[202:205], v[74:77]
	v_mfma_f32_16x16x32_bf16 v[70:73], v[170:173], v[210:213], v[70:73]
	v_mfma_f32_16x16x32_bf16 v[66:69], v[178:181], v[210:213], v[66:69]
	s_nop 0
	s_barrier
	s_add_i32 s22, s50, s25
	v_lshl_add_u64 v[162:163], v[162:163], 0, s[8:9]
	s_mov_b32 m0, s22
	ds_read_b128 v[182:185], v153 offset:49152
	ds_read_b128 v[186:189], v153 offset:50176
	ds_read_b128 v[190:193], v153 offset:51200
	ds_read_b128 v[194:197], v153 offset:52224
	ds_read_b128 v[198:201], v153 offset:53248
	ds_read_b128 v[202:205], v153 offset:54272
	ds_read_b128 v[206:209], v153 offset:55296
	ds_read_b128 v[210:213], v153 offset:56320
	global_load_lds_dwordx4 v[162:163], off
	s_add_i32 m0, s22, 0x2000
	s_add_u32 s20, s20, 0x60080
	v_lshl_add_u64 v[162:163], v[214:215], 0, s[8:9]
	s_addc_u32 s21, s21, 0
	s_add_i32 s22, s51, s25
	global_load_lds_dwordx4 v[162:163], off
	v_lshl_add_u64 v[162:163], s[20:21], 0, v[132:133]
	s_mov_b32 m0, s22
	s_nop 0
	global_load_lds_dwordx4 v[162:163], off
	v_lshl_add_u64 v[162:163], s[20:21], 0, v[136:137]
	s_add_i32 m0, s22, 0x2000
	s_nop 0
	global_load_lds_dwordx4 v[162:163], off
	v_lshl_add_u64 v[162:163], v[216:217], 0, s[8:9]
	s_mov_b32 m0, s34
	s_nop 0
	global_load_lds_dwordx4 v[162:163], off
	v_lshl_add_u64 v[162:163], v[218:219], 0, s[8:9]
	s_mov_b32 m0, s35
	s_nop 0
	global_load_lds_dwordx4 v[162:163], off
	s_waitcnt vmcnt(8)
	s_waitcnt lgkmcnt(0)
	s_barrier
	s_nop 0
	s_waitcnt lgkmcnt(0)
	v_mfma_f32_16x16x32_bf16 v[62:65], v[142:145], v[182:185], v[62:65]
	v_mfma_f32_16x16x32_bf16 v[58:61], v[154:157], v[182:185], v[58:61]
	v_mfma_f32_16x16x32_bf16 v[54:57], v[142:145], v[190:193], v[54:57]
	v_mfma_f32_16x16x32_bf16 v[50:53], v[154:157], v[190:193], v[50:53]
	v_mfma_f32_16x16x32_bf16 v[46:49], v[142:145], v[198:201], v[46:49]
	v_mfma_f32_16x16x32_bf16 v[42:45], v[154:157], v[198:201], v[42:45]
	v_mfma_f32_16x16x32_bf16 v[38:41], v[142:145], v[206:209], v[38:41]
	v_mfma_f32_16x16x32_bf16 v[34:37], v[154:157], v[206:209], v[34:37]
	v_mfma_f32_16x16x32_bf16 v[62:65], v[146:149], v[186:189], v[62:65]
	v_mfma_f32_16x16x32_bf16 v[58:61], v[158:161], v[186:189], v[58:61]
	v_mfma_f32_16x16x32_bf16 v[54:57], v[146:149], v[194:197], v[54:57]
	v_mfma_f32_16x16x32_bf16 v[50:53], v[158:161], v[194:197], v[50:53]
	v_mfma_f32_16x16x32_bf16 v[46:49], v[146:149], v[202:205], v[46:49]
	v_mfma_f32_16x16x32_bf16 v[42:45], v[158:161], v[202:205], v[42:45]
	v_mfma_f32_16x16x32_bf16 v[38:41], v[146:149], v[210:213], v[38:41]
	v_mfma_f32_16x16x32_bf16 v[34:37], v[158:161], v[210:213], v[34:37]
	s_nop 0
	s_nop 0
	v_mfma_f32_16x16x32_bf16 v[30:33], v[166:169], v[182:185], v[30:33]
	v_mfma_f32_16x16x32_bf16 v[26:29], v[174:177], v[182:185], v[26:29]
	v_mfma_f32_16x16x32_bf16 v[22:25], v[166:169], v[190:193], v[22:25]
	v_mfma_f32_16x16x32_bf16 v[18:21], v[174:177], v[190:193], v[18:21]
	v_mfma_f32_16x16x32_bf16 v[14:17], v[166:169], v[198:201], v[14:17]
	v_mfma_f32_16x16x32_bf16 v[10:13], v[174:177], v[198:201], v[10:13]
	v_mfma_f32_16x16x32_bf16 v[6:9], v[166:169], v[206:209], v[6:9]
	v_mfma_f32_16x16x32_bf16 v[2:5], v[174:177], v[206:209], v[2:5]
	v_mfma_f32_16x16x32_bf16 v[30:33], v[170:173], v[186:189], v[30:33]
	v_mfma_f32_16x16x32_bf16 v[26:29], v[178:181], v[186:189], v[26:29]
	v_mfma_f32_16x16x32_bf16 v[22:25], v[170:173], v[194:197], v[22:25]
	v_mfma_f32_16x16x32_bf16 v[18:21], v[178:181], v[194:197], v[18:21]
	v_mfma_f32_16x16x32_bf16 v[14:17], v[170:173], v[202:205], v[14:17]
	v_mfma_f32_16x16x32_bf16 v[10:13], v[178:181], v[202:205], v[10:13]
	v_mfma_f32_16x16x32_bf16 v[6:9], v[170:173], v[210:213], v[6:9]
	v_mfma_f32_16x16x32_bf16 v[2:5], v[178:181], v[210:213], v[2:5]
	s_nop 0
	s_add_u32 s4, s4, 0x100
	s_addc_u32 s5, s5, 0
	s_add_u32 s47, s47, 0x100
	s_addc_u32 s48, s48, 0
	s_cmp_ge_i32 s49, s45
	s_mov_b32 s20, s49
	s_barrier
	s_cbranch_scc0 .LBB0_842
	s_setprio 0
	s_and_b64 vcc, exec, s[10:11]
	s_cbranch_vccz .LBB0_845
	s_barrier

.Lsp_p6:
.LBB0_1019:
	ds_read_b128 v[142:145], v149
	ds_read_b128 v[154:157], v149 offset:1024
	ds_read_b128 v[158:161], v149 offset:2048
	ds_read_b128 v[166:169], v149 offset:3072
	ds_read_b128 v[170:173], v150
	ds_read_b128 v[174:177], v150 offset:1024
	ds_read_b128 v[178:181], v150 offset:2048
	ds_read_b128 v[182:185], v150 offset:3072
	s_add_u32 s28, s26, 0xfff80080
	s_addc_u32 s29, s27, -1
	s_cmp_eq_u32 s49, 28
	s_cselect_b32 s31, s1, s29
	s_cselect_b32 s30, s15, s28
	s_cselect_b32 s29, s17, s48
	s_cselect_b32 s28, s46, s47
	v_lshl_add_u64 v[162:163], s[26:27], 0, v[138:139]
	s_add_i32 m0, s34, 0xc000
	ds_read_b128 v[186:189], v151
	ds_read_b128 v[190:193], v151 offset:1024
	ds_read_b128 v[194:197], v151 offset:2048
	ds_read_b128 v[198:201], v151 offset:3072
	ds_read_b128 v[202:205], v151 offset:4096
	ds_read_b128 v[206:209], v151 offset:5120
	ds_read_b128 v[210:213], v151 offset:6144
	ds_read_b128 v[214:217], v151 offset:7168
	global_load_lds_dwordx4 v[162:163], off
	v_lshl_add_u64 v[162:163], s[26:27], 0, v[140:141]
	s_add_i32 m0, s34, 0xe000
	s_nop 0
	global_load_lds_dwordx4 v[162:163], off
	s_waitcnt vmcnt(8)
	s_waitcnt lgkmcnt(0)
	s_barrier
	s_nop 0
	s_waitcnt lgkmcnt(0)
	v_mfma_f32_16x16x32_bf16 v[126:129], v[142:145], v[186:189], v[126:129]
	v_mfma_f32_16x16x32_bf16 v[122:125], v[158:161], v[186:189], v[122:125]
	v_mfma_f32_16x16x32_bf16 v[110:113], v[142:145], v[194:197], v[110:113]
	v_mfma_f32_16x16x32_bf16 v[106:109], v[158:161], v[194:197], v[106:109]
	v_mfma_f32_16x16x32_bf16 v[94:97], v[142:145], v[202:205], v[94:97]
	v_mfma_f32_16x16x32_bf16 v[90:93], v[158:161], v[202:205], v[90:93]
	v_mfma_f32_16x16x32_bf16 v[78:81], v[142:145], v[210:213], v[78:81]
	v_mfma_f32_16x16x32_bf16 v[74:77], v[158:161], v[210:213], v[74:77]
	v_mfma_f32_16x16x32_bf16 v[126:129], v[154:157], v[190:193], v[126:129]
	v_mfma_f32_16x16x32_bf16 v[122:125], v[166:169], v[190:193], v[122:125]
	v_mfma_f32_16x16x32_bf16 v[110:113], v[154:157], v[198:201], v[110:113]
	v_mfma_f32_16x16x32_bf16 v[106:109], v[166:169], v[198:201], v[106:109]
	v_mfma_f32_16x16x32_bf16 v[94:97], v[154:157], v[206:209], v[94:97]
	v_mfma_f32_16x16x32_bf16 v[90:93], v[166:169], v[206:209], v[90:93]
	v_mfma_f32_16x16x32_bf16 v[78:81], v[154:157], v[214:217], v[78:81]
	v_mfma_f32_16x16x32_bf16 v[74:77], v[166:169], v[214:217], v[74:77]
	s_nop 0
	s_nop 0
	v_mfma_f32_16x16x32_bf16 v[118:121], v[170:173], v[186:189], v[118:121]
	v_mfma_f32_16x16x32_bf16 v[114:117], v[178:181], v[186:189], v[114:117]
	v_mfma_f32_16x16x32_bf16 v[102:105], v[170:173], v[194:197], v[102:105]
	v_mfma_f32_16x16x32_bf16 v[98:101], v[178:181], v[194:197], v[98:101]
	v_mfma_f32_16x16x32_bf16 v[86:89], v[170:173], v[202:205], v[86:89]
	v_mfma_f32_16x16x32_bf16 v[82:85], v[178:181], v[202:205], v[82:85]
	v_mfma_f32_16x16x32_bf16 v[70:73], v[170:173], v[210:213], v[70:73]
	v_mfma_f32_16x16x32_bf16 v[66:69], v[178:181], v[210:213], v[66:69]
	v_mfma_f32_16x16x32_bf16 v[118:121], v[174:177], v[190:193], v[118:121]
	v_mfma_f32_16x16x32_bf16 v[114:117], v[182:185], v[190:193], v[114:117]
	v_mfma_f32_16x16x32_bf16 v[102:105], v[174:177], v[198:201], v[102:105]
	v_mfma_f32_16x16x32_bf16 v[98:101], v[182:185], v[198:201], v[98:101]
	v_mfma_f32_16x16x32_bf16 v[86:89], v[174:177], v[206:209], v[86:89]
	v_mfma_f32_16x16x32_bf16 v[82:85], v[182:185], v[206:209], v[82:85]
	v_mfma_f32_16x16x32_bf16 v[70:73], v[174:177], v[214:217], v[70:73]
	v_mfma_f32_16x16x32_bf16 v[66:69], v[182:185], v[214:217], v[66:69]
	s_nop 0
	s_barrier
	s_add_i32 s50, s44, s25
	v_lshl_add_u64 v[162:163], s[28:29], 0, v[132:133]
	s_mov_b32 m0, s50
	ds_read_b128 v[186:189], v151 offset:16384
	ds_read_b128 v[190:193], v151 offset:17408
	ds_read_b128 v[194:197], v151 offset:18432
	ds_read_b128 v[198:201], v151 offset:19456
	ds_read_b128 v[202:205], v151 offset:20480
	ds_read_b128 v[206:209], v151 offset:21504
	ds_read_b128 v[210:213], v151 offset:22528
	ds_read_b128 v[214:217], v151 offset:23552
	global_load_lds_dwordx4 v[162:163], off
	s_add_i32 m0, s50, 0x2000
	s_add_u32 s50, s28, 0x80000
	v_lshl_add_u64 v[218:219], s[28:29], 0, v[136:137]
	s_addc_u32 s51, s29, 0
	s_add_i32 s52, s45, s25
	global_load_lds_dwordx4 v[218:219], off
	v_lshl_add_u64 v[220:221], s[50:51], 0, v[132:133]
	s_mov_b32 m0, s52
	v_lshl_add_u64 v[222:223], s[30:31], 0, v[134:135]
	global_load_lds_dwordx4 v[220:221], off
	v_lshl_add_u64 v[220:221], s[50:51], 0, v[136:137]
	s_add_i32 m0, s52, 0x2000
	s_nop 0
	global_load_lds_dwordx4 v[220:221], off
	v_lshl_add_u64 v[220:221], s[30:31], 0, v[130:131]
	s_mov_b32 m0, s34
	s_nop 0
	global_load_lds_dwordx4 v[220:221], off
	s_mov_b32 m0, s35
	s_nop 0
	global_load_lds_dwordx4 v[222:223], off
	s_waitcnt vmcnt(8)
	s_waitcnt lgkmcnt(0)
	s_barrier
	s_nop 0
	s_waitcnt lgkmcnt(0)
	v_mfma_f32_16x16x32_bf16 v[62:65], v[142:145], v[186:189], v[62:65]
	v_mfma_f32_16x16x32_bf16 v[58:61], v[158:161], v[186:189], v[58:61]
	v_mfma_f32_16x16x32_bf16 v[46:49], v[142:145], v[194:197], v[46:49]
	v_mfma_f32_16x16x32_bf16 v[42:45], v[158:161], v[194:197], v[42:45]
	v_mfma_f32_16x16x32_bf16 v[30:33], v[142:145], v[202:205], v[30:33]
	v_mfma_f32_16x16x32_bf16 v[26:29], v[158:161], v[202:205], v[26:29]
	v_mfma_f32_16x16x32_bf16 v[14:17], v[142:145], v[210:213], v[14:17]
	v_mfma_f32_16x16x32_bf16 v[10:13], v[158:161], v[210:213], v[10:13]
	v_mfma_f32_16x16x32_bf16 v[62:65], v[154:157], v[190:193], v[62:65]
	v_mfma_f32_16x16x32_bf16 v[58:61], v[166:169], v[190:193], v[58:61]
	v_mfma_f32_16x16x32_bf16 v[46:49], v[154:157], v[198:201], v[46:49]
	v_mfma_f32_16x16x32_bf16 v[42:45], v[166:169], v[198:201], v[42:45]
	v_mfma_f32_16x16x32_bf16 v[30:33], v[154:157], v[206:209], v[30:33]
	v_mfma_f32_16x16x32_bf16 v[26:29], v[166:169], v[206:209], v[26:29]
	v_mfma_f32_16x16x32_bf16 v[14:17], v[154:157], v[214:217], v[14:17]
	v_mfma_f32_16x16x32_bf16 v[10:13], v[166:169], v[214:217], v[10:13]
	s_nop 0
	s_nop 0
	v_mfma_f32_16x16x32_bf16 v[54:57], v[170:173], v[186:189], v[54:57]
	v_mfma_f32_16x16x32_bf16 v[50:53], v[178:181], v[186:189], v[50:53]
	v_mfma_f32_16x16x32_bf16 v[38:41], v[170:173], v[194:197], v[38:41]
	v_mfma_f32_16x16x32_bf16 v[34:37], v[178:181], v[194:197], v[34:37]
	v_mfma_f32_16x16x32_bf16 v[22:25], v[170:173], v[202:205], v[22:25]
	v_mfma_f32_16x16x32_bf16 v[18:21], v[178:181], v[202:205], v[18:21]
	v_mfma_f32_16x16x32_bf16 v[6:9], v[170:173], v[210:213], v[6:9]
	v_mfma_f32_16x16x32_bf16 v[2:5], v[178:181], v[210:213], v[2:5]
	v_mfma_f32_16x16x32_bf16 v[54:57], v[174:177], v[190:193], v[54:57]
	v_mfma_f32_16x16x32_bf16 v[50:53], v[182:185], v[190:193], v[50:53]
	v_mfma_f32_16x16x32_bf16 v[38:41], v[174:177], v[198:201], v[38:41]
	v_mfma_f32_16x16x32_bf16 v[34:37], v[182:185], v[198:201], v[34:37]
	v_mfma_f32_16x16x32_bf16 v[22:25], v[174:177], v[206:209], v[22:25]
	v_mfma_f32_16x16x32_bf16 v[18:21], v[182:185], v[206:209], v[18:21]
	v_mfma_f32_16x16x32_bf16 v[6:9], v[174:177], v[214:217], v[6:9]
	v_mfma_f32_16x16x32_bf16 v[2:5], v[182:185], v[214:217], v[2:5]
	s_nop 0
	s_barrier
	s_add_i32 s50, 0, 0x18000
	v_add_u32_e32 v153, s50, v148
	s_add_i32 s51, 0, 0x1c000
	ds_read_b128 v[142:145], v153
	ds_read_b128 v[154:157], v153 offset:1024
	ds_read_b128 v[158:161], v153 offset:2048
	ds_read_b128 v[166:169], v153 offset:3072
	v_add_u32_e32 v153, s51, v148
	ds_read_b128 v[170:173], v153
	ds_read_b128 v[174:177], v153 offset:1024
	ds_read_b128 v[178:181], v153 offset:2048
	ds_read_b128 v[182:185], v153 offset:3072
	s_add_u32 s30, s30, 0x80000
	s_addc_u32 s31, s31, 0
	s_mov_b32 m0, s36
	v_lshl_add_u64 v[224:225], s[30:31], 0, v[130:131]
	ds_read_b128 v[186:189], v151 offset:32768
	ds_read_b128 v[190:193], v151 offset:33792
	ds_read_b128 v[194:197], v151 offset:34816
	ds_read_b128 v[198:201], v151 offset:35840
	ds_read_b128 v[202:205], v151 offset:36864
	ds_read_b128 v[206:209], v151 offset:37888
	ds_read_b128 v[210:213], v151 offset:38912
	ds_read_b128 v[214:217], v151 offset:39936
	global_load_lds_dwordx4 v[224:225], off
	v_lshl_add_u64 v[224:225], s[30:31], 0, v[134:135]
	s_mov_b32 m0, s37
	s_nop 0
	global_load_lds_dwordx4 v[224:225], off
	s_waitcnt vmcnt(8)
	s_waitcnt lgkmcnt(0)
	s_barrier
	s_nop 0
	s_waitcnt lgkmcnt(0)
	v_mfma_f32_16x16x32_bf16 v[126:129], v[142:145], v[186:189], v[126:129]
	v_mfma_f32_16x16x32_bf16 v[122:125], v[158:161], v[186:189], v[122:125]
	v_mfma_f32_16x16x32_bf16 v[110:113], v[142:145], v[194:197], v[110:113]
	v_mfma_f32_16x16x32_bf16 v[106:109], v[158:161], v[194:197], v[106:109]
	v_mfma_f32_16x16x32_bf16 v[94:97], v[142:145], v[202:205], v[94:97]
	v_mfma_f32_16x16x32_bf16 v[90:93], v[158:161], v[202:205], v[90:93]
	v_mfma_f32_16x16x32_bf16 v[78:81], v[142:145], v[210:213], v[78:81]
	v_mfma_f32_16x16x32_bf16 v[74:77], v[158:161], v[210:213], v[74:77]
	v_mfma_f32_16x16x32_bf16 v[126:129], v[154:157], v[190:193], v[126:129]
	v_mfma_f32_16x16x32_bf16 v[122:125], v[166:169], v[190:193], v[122:125]
	v_mfma_f32_16x16x32_bf16 v[110:113], v[154:157], v[198:201], v[110:113]
	v_mfma_f32_16x16x32_bf16 v[106:109], v[166:169], v[198:201], v[106:109]
	v_mfma_f32_16x16x32_bf16 v[94:97], v[154:157], v[206:209], v[94:97]
	v_mfma_f32_16x16x32_bf16 v[90:93], v[166:169], v[206:209], v[90:93]
	v_mfma_f32_16x16x32_bf16 v[78:81], v[154:157], v[214:217], v[78:81]
	v_mfma_f32_16x16x32_bf16 v[74:77], v[166:169], v[214:217], v[74:77]
	s_nop 0
	s_nop 0
	v_mfma_f32_16x16x32_bf16 v[118:121], v[170:173], v[186:189], v[118:121]
	v_mfma_f32_16x16x32_bf16 v[114:117], v[178:181], v[186:189], v[114:117]
	v_mfma_f32_16x16x32_bf16 v[102:105], v[170:173], v[194:197], v[102:105]
	v_mfma_f32_16x16x32_bf16 v[98:101], v[178:181], v[194:197], v[98:101]
	v_mfma_f32_16x16x32_bf16 v[86:89], v[170:173], v[202:205], v[86:89]
	v_mfma_f32_16x16x32_bf16 v[82:85], v[178:181], v[202:205], v[82:85]
	v_mfma_f32_16x16x32_bf16 v[70:73], v[170:173], v[210:213], v[70:73]
	v_mfma_f32_16x16x32_bf16 v[66:69], v[178:181], v[210:213], v[66:69]
	v_mfma_f32_16x16x32_bf16 v[118:121], v[174:177], v[190:193], v[118:121]
	v_mfma_f32_16x16x32_bf16 v[114:117], v[182:185], v[190:193], v[114:117]
	v_mfma_f32_16x16x32_bf16 v[102:105], v[174:177], v[198:201], v[102:105]
	v_mfma_f32_16x16x32_bf16 v[98:101], v[182:185], v[198:201], v[98:101]
	v_mfma_f32_16x16x32_bf16 v[86:89], v[174:177], v[206:209], v[86:89]
	v_mfma_f32_16x16x32_bf16 v[82:85], v[182:185], v[206:209], v[82:85]
	v_mfma_f32_16x16x32_bf16 v[70:73], v[174:177], v[214:217], v[70:73]
	v_mfma_f32_16x16x32_bf16 v[66:69], v[182:185], v[214:217], v[66:69]
	s_nop 0
	s_barrier
	s_add_i32 s30, s50, s25
	v_lshl_add_u64 v[162:163], v[162:163], 0, s[8:9]
	s_mov_b32 m0, s30
	ds_read_b128 v[186:189], v151 offset:49152
	ds_read_b128 v[190:193], v151 offset:50176
	ds_read_b128 v[194:197], v151 offset:51200
	ds_read_b128 v[198:201], v151 offset:52224
	ds_read_b128 v[202:205], v151 offset:53248
	ds_read_b128 v[206:209], v151 offset:54272
	ds_read_b128 v[210:213], v151 offset:55296
	ds_read_b128 v[214:217], v151 offset:56320
	global_load_lds_dwordx4 v[162:163], off
	s_add_i32 m0, s30, 0x2000
	s_add_u32 s28, s28, 0x80080
	v_lshl_add_u64 v[162:163], v[218:219], 0, s[8:9]
	s_addc_u32 s29, s29, 0
	s_add_i32 s30, s51, s25
	global_load_lds_dwordx4 v[162:163], off
	v_lshl_add_u64 v[162:163], s[28:29], 0, v[132:133]
	s_mov_b32 m0, s30
	s_nop 0
	global_load_lds_dwordx4 v[162:163], off
	v_lshl_add_u64 v[162:163], s[28:29], 0, v[136:137]
	s_add_i32 m0, s30, 0x2000
	s_nop 0
	global_load_lds_dwordx4 v[162:163], off
	v_lshl_add_u64 v[162:163], v[220:221], 0, s[8:9]
	s_mov_b32 m0, s41
	s_nop 0
	global_load_lds_dwordx4 v[162:163], off
	v_lshl_add_u64 v[162:163], v[222:223], 0, s[8:9]
	s_mov_b32 m0, s42
	s_nop 0
	global_load_lds_dwordx4 v[162:163], off
	s_waitcnt vmcnt(8)
	s_waitcnt lgkmcnt(0)
	s_barrier
	s_nop 0
	s_waitcnt lgkmcnt(0)
	v_mfma_f32_16x16x32_bf16 v[62:65], v[142:145], v[186:189], v[62:65]
	v_mfma_f32_16x16x32_bf16 v[58:61], v[158:161], v[186:189], v[58:61]
	v_mfma_f32_16x16x32_bf16 v[46:49], v[142:145], v[194:197], v[46:49]
	v_mfma_f32_16x16x32_bf16 v[42:45], v[158:161], v[194:197], v[42:45]
	v_mfma_f32_16x16x32_bf16 v[30:33], v[142:145], v[202:205], v[30:33]
	v_mfma_f32_16x16x32_bf16 v[26:29], v[158:161], v[202:205], v[26:29]
	v_mfma_f32_16x16x32_bf16 v[14:17], v[142:145], v[210:213], v[14:17]
	v_mfma_f32_16x16x32_bf16 v[10:13], v[158:161], v[210:213], v[10:13]
	v_mfma_f32_16x16x32_bf16 v[62:65], v[154:157], v[190:193], v[62:65]
	v_mfma_f32_16x16x32_bf16 v[58:61], v[166:169], v[190:193], v[58:61]
	v_mfma_f32_16x16x32_bf16 v[46:49], v[154:157], v[198:201], v[46:49]
	v_mfma_f32_16x16x32_bf16 v[42:45], v[166:169], v[198:201], v[42:45]
	v_mfma_f32_16x16x32_bf16 v[30:33], v[154:157], v[206:209], v[30:33]
	v_mfma_f32_16x16x32_bf16 v[26:29], v[166:169], v[206:209], v[26:29]
	v_mfma_f32_16x16x32_bf16 v[14:17], v[154:157], v[214:217], v[14:17]
	v_mfma_f32_16x16x32_bf16 v[10:13], v[166:169], v[214:217], v[10:13]
	s_nop 0
	s_nop 0
	v_mfma_f32_16x16x32_bf16 v[54:57], v[170:173], v[186:189], v[54:57]
	v_mfma_f32_16x16x32_bf16 v[50:53], v[178:181], v[186:189], v[50:53]
	v_mfma_f32_16x16x32_bf16 v[38:41], v[170:173], v[194:197], v[38:41]
	v_mfma_f32_16x16x32_bf16 v[34:37], v[178:181], v[194:197], v[34:37]
	v_mfma_f32_16x16x32_bf16 v[22:25], v[170:173], v[202:205], v[22:25]
	v_mfma_f32_16x16x32_bf16 v[18:21], v[178:181], v[202:205], v[18:21]
	v_mfma_f32_16x16x32_bf16 v[6:9], v[170:173], v[210:213], v[6:9]
	v_mfma_f32_16x16x32_bf16 v[2:5], v[178:181], v[210:213], v[2:5]
	v_mfma_f32_16x16x32_bf16 v[54:57], v[174:177], v[190:193], v[54:57]
	v_mfma_f32_16x16x32_bf16 v[50:53], v[182:185], v[190:193], v[50:53]
	v_mfma_f32_16x16x32_bf16 v[38:41], v[174:177], v[198:201], v[38:41]
	v_mfma_f32_16x16x32_bf16 v[34:37], v[182:185], v[198:201], v[34:37]
	v_mfma_f32_16x16x32_bf16 v[22:25], v[174:177], v[206:209], v[22:25]
	v_mfma_f32_16x16x32_bf16 v[18:21], v[182:185], v[206:209], v[18:21]
	v_mfma_f32_16x16x32_bf16 v[6:9], v[174:177], v[214:217], v[6:9]
	v_mfma_f32_16x16x32_bf16 v[2:5], v[182:185], v[214:217], v[2:5]
	s_nop 0
	s_add_i32 s49, s49, 2
	s_add_u32 s26, s26, 0x100
	s_addc_u32 s27, s27, 0
	s_add_u32 s47, s47, 0x100
	s_addc_u32 s48, s48, 0
	s_cmp_gt_u32 s49, 29
	s_barrier
	s_cbranch_scc0 .LBB0_1019
	s_setprio 0
	s_and_b64 vcc, exec, s[10:11]
	s_cbranch_vccz .LBB0_1022
	s_barrier

.Lsp_p9:
.LBB0_1220:
	ds_read_b128 v[142:145], v149
	ds_read_b128 v[154:157], v149 offset:1024
	ds_read_b128 v[158:161], v149 offset:2048
	ds_read_b128 v[166:169], v149 offset:3072
	ds_read_b128 v[170:173], v150
	ds_read_b128 v[174:177], v150 offset:1024
	ds_read_b128 v[178:181], v150 offset:2048
	ds_read_b128 v[182:185], v150 offset:3072
	s_add_u32 s30, s28, 0xfffe0080
	s_addc_u32 s31, s29, -1
	s_cmp_eq_u32 s51, 4
	s_cselect_b32 s35, s1, s31
	s_cselect_b32 s34, s17, s30
	s_cselect_b32 s31, s19, s50
	s_cselect_b32 s30, s48, s49
	v_lshl_add_u64 v[162:163], s[28:29], 0, v[138:139]
	s_add_i32 m0, s27, 0xc000
	ds_read_b128 v[186:189], v151
	ds_read_b128 v[190:193], v151 offset:1024
	ds_read_b128 v[194:197], v151 offset:2048
	ds_read_b128 v[198:201], v151 offset:3072
	ds_read_b128 v[202:205], v151 offset:4096
	ds_read_b128 v[206:209], v151 offset:5120
	ds_read_b128 v[210:213], v151 offset:6144
	ds_read_b128 v[214:217], v151 offset:7168
	global_load_lds_dwordx4 v[162:163], off
	v_lshl_add_u64 v[162:163], s[28:29], 0, v[140:141]
	s_add_i32 m0, s27, 0xe000
	s_nop 0
	global_load_lds_dwordx4 v[162:163], off
	s_waitcnt vmcnt(8)
	s_waitcnt lgkmcnt(0)
	s_barrier
	s_nop 0
	s_waitcnt lgkmcnt(0)
	v_mfma_f32_16x16x32_bf16 v[126:129], v[142:145], v[186:189], v[126:129]
	v_mfma_f32_16x16x32_bf16 v[122:125], v[158:161], v[186:189], v[122:125]
	v_mfma_f32_16x16x32_bf16 v[110:113], v[142:145], v[194:197], v[110:113]
	v_mfma_f32_16x16x32_bf16 v[106:109], v[158:161], v[194:197], v[106:109]
	v_mfma_f32_16x16x32_bf16 v[94:97], v[142:145], v[202:205], v[94:97]
	v_mfma_f32_16x16x32_bf16 v[90:93], v[158:161], v[202:205], v[90:93]
	v_mfma_f32_16x16x32_bf16 v[78:81], v[142:145], v[210:213], v[78:81]
	v_mfma_f32_16x16x32_bf16 v[74:77], v[158:161], v[210:213], v[74:77]
	v_mfma_f32_16x16x32_bf16 v[126:129], v[154:157], v[190:193], v[126:129]
	v_mfma_f32_16x16x32_bf16 v[122:125], v[166:169], v[190:193], v[122:125]
	v_mfma_f32_16x16x32_bf16 v[110:113], v[154:157], v[198:201], v[110:113]
	v_mfma_f32_16x16x32_bf16 v[106:109], v[166:169], v[198:201], v[106:109]
	v_mfma_f32_16x16x32_bf16 v[94:97], v[154:157], v[206:209], v[94:97]
	v_mfma_f32_16x16x32_bf16 v[90:93], v[166:169], v[206:209], v[90:93]
	v_mfma_f32_16x16x32_bf16 v[78:81], v[154:157], v[214:217], v[78:81]
	v_mfma_f32_16x16x32_bf16 v[74:77], v[166:169], v[214:217], v[74:77]
	s_nop 0
	s_nop 0
	v_mfma_f32_16x16x32_bf16 v[118:121], v[170:173], v[186:189], v[118:121]
	v_mfma_f32_16x16x32_bf16 v[114:117], v[178:181], v[186:189], v[114:117]
	v_mfma_f32_16x16x32_bf16 v[102:105], v[170:173], v[194:197], v[102:105]
	v_mfma_f32_16x16x32_bf16 v[98:101], v[178:181], v[194:197], v[98:101]
	v_mfma_f32_16x16x32_bf16 v[86:89], v[170:173], v[202:205], v[86:89]
	v_mfma_f32_16x16x32_bf16 v[82:85], v[178:181], v[202:205], v[82:85]
	v_mfma_f32_16x16x32_bf16 v[70:73], v[170:173], v[210:213], v[70:73]
	v_mfma_f32_16x16x32_bf16 v[66:69], v[178:181], v[210:213], v[66:69]
	v_mfma_f32_16x16x32_bf16 v[118:121], v[174:177], v[190:193], v[118:121]
	v_mfma_f32_16x16x32_bf16 v[114:117], v[182:185], v[190:193], v[114:117]
	v_mfma_f32_16x16x32_bf16 v[102:105], v[174:177], v[198:201], v[102:105]
	v_mfma_f32_16x16x32_bf16 v[98:101], v[182:185], v[198:201], v[98:101]
	v_mfma_f32_16x16x32_bf16 v[86:89], v[174:177], v[206:209], v[86:89]
	v_mfma_f32_16x16x32_bf16 v[82:85], v[182:185], v[206:209], v[82:85]
	v_mfma_f32_16x16x32_bf16 v[70:73], v[174:177], v[214:217], v[70:73]
	v_mfma_f32_16x16x32_bf16 v[66:69], v[182:185], v[214:217], v[66:69]
	s_nop 0
	s_barrier
	s_add_i32 s52, s46, s2
	v_lshl_add_u64 v[162:163], s[30:31], 0, v[132:133]
	s_mov_b32 m0, s52
	ds_read_b128 v[186:189], v151 offset:16384
	ds_read_b128 v[190:193], v151 offset:17408
	ds_read_b128 v[194:197], v151 offset:18432
	ds_read_b128 v[198:201], v151 offset:19456
	ds_read_b128 v[202:205], v151 offset:20480
	ds_read_b128 v[206:209], v151 offset:21504
	ds_read_b128 v[210:213], v151 offset:22528
	ds_read_b128 v[214:217], v151 offset:23552
	global_load_lds_dwordx4 v[162:163], off
	s_add_i32 m0, s52, 0x2000
	s_add_u32 s52, s30, 0x20000
	v_lshl_add_u64 v[218:219], s[30:31], 0, v[136:137]
	s_addc_u32 s53, s31, 0
	s_add_i32 s54, s47, s2
	global_load_lds_dwordx4 v[218:219], off
	v_lshl_add_u64 v[220:221], s[52:53], 0, v[132:133]
	s_mov_b32 m0, s54
	v_lshl_add_u64 v[222:223], s[34:35], 0, v[134:135]
	global_load_lds_dwordx4 v[220:221], off
	v_lshl_add_u64 v[220:221], s[52:53], 0, v[136:137]
	s_add_i32 m0, s54, 0x2000
	s_nop 0
	global_load_lds_dwordx4 v[220:221], off
	v_lshl_add_u64 v[220:221], s[34:35], 0, v[130:131]
	s_mov_b32 m0, s27
	s_nop 0
	global_load_lds_dwordx4 v[220:221], off
	s_mov_b32 m0, s37
	s_nop 0
	global_load_lds_dwordx4 v[222:223], off
	s_waitcnt vmcnt(8)
	s_waitcnt lgkmcnt(0)
	s_barrier
	s_nop 0
	s_waitcnt lgkmcnt(0)
	v_mfma_f32_16x16x32_bf16 v[62:65], v[142:145], v[186:189], v[62:65]
	v_mfma_f32_16x16x32_bf16 v[58:61], v[158:161], v[186:189], v[58:61]
	v_mfma_f32_16x16x32_bf16 v[46:49], v[142:145], v[194:197], v[46:49]
	v_mfma_f32_16x16x32_bf16 v[42:45], v[158:161], v[194:197], v[42:45]
	v_mfma_f32_16x16x32_bf16 v[30:33], v[142:145], v[202:205], v[30:33]
	v_mfma_f32_16x16x32_bf16 v[26:29], v[158:161], v[202:205], v[26:29]
	v_mfma_f32_16x16x32_bf16 v[14:17], v[142:145], v[210:213], v[14:17]
	v_mfma_f32_16x16x32_bf16 v[10:13], v[158:161], v[210:213], v[10:13]
	v_mfma_f32_16x16x32_bf16 v[62:65], v[154:157], v[190:193], v[62:65]
	v_mfma_f32_16x16x32_bf16 v[58:61], v[166:169], v[190:193], v[58:61]
	v_mfma_f32_16x16x32_bf16 v[46:49], v[154:157], v[198:201], v[46:49]
	v_mfma_f32_16x16x32_bf16 v[42:45], v[166:169], v[198:201], v[42:45]
	v_mfma_f32_16x16x32_bf16 v[30:33], v[154:157], v[206:209], v[30:33]
	v_mfma_f32_16x16x32_bf16 v[26:29], v[166:169], v[206:209], v[26:29]
	v_mfma_f32_16x16x32_bf16 v[14:17], v[154:157], v[214:217], v[14:17]
	v_mfma_f32_16x16x32_bf16 v[10:13], v[166:169], v[214:217], v[10:13]
	s_nop 0
	s_nop 0
	v_mfma_f32_16x16x32_bf16 v[54:57], v[170:173], v[186:189], v[54:57]
	v_mfma_f32_16x16x32_bf16 v[50:53], v[178:181], v[186:189], v[50:53]
	v_mfma_f32_16x16x32_bf16 v[38:41], v[170:173], v[194:197], v[38:41]
	v_mfma_f32_16x16x32_bf16 v[34:37], v[178:181], v[194:197], v[34:37]
	v_mfma_f32_16x16x32_bf16 v[22:25], v[170:173], v[202:205], v[22:25]
	v_mfma_f32_16x16x32_bf16 v[18:21], v[178:181], v[202:205], v[18:21]
	v_mfma_f32_16x16x32_bf16 v[6:9], v[170:173], v[210:213], v[6:9]
	v_mfma_f32_16x16x32_bf16 v[2:5], v[178:181], v[210:213], v[2:5]
	v_mfma_f32_16x16x32_bf16 v[54:57], v[174:177], v[190:193], v[54:57]
	v_mfma_f32_16x16x32_bf16 v[50:53], v[182:185], v[190:193], v[50:53]
	v_mfma_f32_16x16x32_bf16 v[38:41], v[174:177], v[198:201], v[38:41]
	v_mfma_f32_16x16x32_bf16 v[34:37], v[182:185], v[198:201], v[34:37]
	v_mfma_f32_16x16x32_bf16 v[22:25], v[174:177], v[206:209], v[22:25]
	v_mfma_f32_16x16x32_bf16 v[18:21], v[182:185], v[206:209], v[18:21]
	v_mfma_f32_16x16x32_bf16 v[6:9], v[174:177], v[214:217], v[6:9]
	v_mfma_f32_16x16x32_bf16 v[2:5], v[182:185], v[214:217], v[2:5]
	s_nop 0
	s_barrier
	s_add_i32 s52, 0, 0x18000
	v_add_u32_e32 v153, s52, v148
	s_add_i32 s53, 0, 0x1c000
	ds_read_b128 v[142:145], v153
	ds_read_b128 v[154:157], v153 offset:1024
	ds_read_b128 v[158:161], v153 offset:2048
	ds_read_b128 v[166:169], v153 offset:3072
	v_add_u32_e32 v153, s53, v148
	ds_read_b128 v[170:173], v153
	ds_read_b128 v[174:177], v153 offset:1024
	ds_read_b128 v[178:181], v153 offset:2048
	ds_read_b128 v[182:185], v153 offset:3072
	s_add_u32 s34, s34, 0x20000
	s_addc_u32 s35, s35, 0
	s_mov_b32 m0, s38
	v_lshl_add_u64 v[224:225], s[34:35], 0, v[130:131]
	ds_read_b128 v[186:189], v151 offset:32768
	ds_read_b128 v[190:193], v151 offset:33792
	ds_read_b128 v[194:197], v151 offset:34816
	ds_read_b128 v[198:201], v151 offset:35840
	ds_read_b128 v[202:205], v151 offset:36864
	ds_read_b128 v[206:209], v151 offset:37888
	ds_read_b128 v[210:213], v151 offset:38912
	ds_read_b128 v[214:217], v151 offset:39936
	global_load_lds_dwordx4 v[224:225], off
	v_lshl_add_u64 v[224:225], s[34:35], 0, v[134:135]
	s_mov_b32 m0, s39
	s_nop 0
	global_load_lds_dwordx4 v[224:225], off
	s_waitcnt vmcnt(8)
	s_waitcnt lgkmcnt(0)
	s_barrier
	s_nop 0
	s_waitcnt lgkmcnt(0)
	v_mfma_f32_16x16x32_bf16 v[126:129], v[142:145], v[186:189], v[126:129]
	v_mfma_f32_16x16x32_bf16 v[122:125], v[158:161], v[186:189], v[122:125]
	v_mfma_f32_16x16x32_bf16 v[110:113], v[142:145], v[194:197], v[110:113]
	v_mfma_f32_16x16x32_bf16 v[106:109], v[158:161], v[194:197], v[106:109]
	v_mfma_f32_16x16x32_bf16 v[94:97], v[142:145], v[202:205], v[94:97]
	v_mfma_f32_16x16x32_bf16 v[90:93], v[158:161], v[202:205], v[90:93]
	v_mfma_f32_16x16x32_bf16 v[78:81], v[142:145], v[210:213], v[78:81]
	v_mfma_f32_16x16x32_bf16 v[74:77], v[158:161], v[210:213], v[74:77]
	v_mfma_f32_16x16x32_bf16 v[126:129], v[154:157], v[190:193], v[126:129]
	v_mfma_f32_16x16x32_bf16 v[122:125], v[166:169], v[190:193], v[122:125]
	v_mfma_f32_16x16x32_bf16 v[110:113], v[154:157], v[198:201], v[110:113]
	v_mfma_f32_16x16x32_bf16 v[106:109], v[166:169], v[198:201], v[106:109]
	v_mfma_f32_16x16x32_bf16 v[94:97], v[154:157], v[206:209], v[94:97]
	v_mfma_f32_16x16x32_bf16 v[90:93], v[166:169], v[206:209], v[90:93]
	v_mfma_f32_16x16x32_bf16 v[78:81], v[154:157], v[214:217], v[78:81]
	v_mfma_f32_16x16x32_bf16 v[74:77], v[166:169], v[214:217], v[74:77]
	s_nop 0
	s_nop 0
	v_mfma_f32_16x16x32_bf16 v[118:121], v[170:173], v[186:189], v[118:121]
	v_mfma_f32_16x16x32_bf16 v[114:117], v[178:181], v[186:189], v[114:117]
	v_mfma_f32_16x16x32_bf16 v[102:105], v[170:173], v[194:197], v[102:105]
	v_mfma_f32_16x16x32_bf16 v[98:101], v[178:181], v[194:197], v[98:101]
	v_mfma_f32_16x16x32_bf16 v[86:89], v[170:173], v[202:205], v[86:89]
	v_mfma_f32_16x16x32_bf16 v[82:85], v[178:181], v[202:205], v[82:85]
	v_mfma_f32_16x16x32_bf16 v[70:73], v[170:173], v[210:213], v[70:73]
	v_mfma_f32_16x16x32_bf16 v[66:69], v[178:181], v[210:213], v[66:69]
	v_mfma_f32_16x16x32_bf16 v[118:121], v[174:177], v[190:193], v[118:121]
	v_mfma_f32_16x16x32_bf16 v[114:117], v[182:185], v[190:193], v[114:117]
	v_mfma_f32_16x16x32_bf16 v[102:105], v[174:177], v[198:201], v[102:105]
	v_mfma_f32_16x16x32_bf16 v[98:101], v[182:185], v[198:201], v[98:101]
	v_mfma_f32_16x16x32_bf16 v[86:89], v[174:177], v[206:209], v[86:89]
	v_mfma_f32_16x16x32_bf16 v[82:85], v[182:185], v[206:209], v[82:85]
	v_mfma_f32_16x16x32_bf16 v[70:73], v[174:177], v[214:217], v[70:73]
	v_mfma_f32_16x16x32_bf16 v[66:69], v[182:185], v[214:217], v[66:69]
	s_nop 0
	s_barrier
	s_add_i32 s34, s52, s2
	v_lshl_add_u64 v[162:163], v[162:163], 0, s[10:11]
	s_mov_b32 m0, s34
	ds_read_b128 v[186:189], v151 offset:49152
	ds_read_b128 v[190:193], v151 offset:50176
	ds_read_b128 v[194:197], v151 offset:51200
	ds_read_b128 v[198:201], v151 offset:52224
	ds_read_b128 v[202:205], v151 offset:53248
	ds_read_b128 v[206:209], v151 offset:54272
	ds_read_b128 v[210:213], v151 offset:55296
	ds_read_b128 v[214:217], v151 offset:56320
	global_load_lds_dwordx4 v[162:163], off
	s_add_i32 m0, s34, 0x2000
	s_add_u32 s30, s30, 0x20080
	v_lshl_add_u64 v[162:163], v[218:219], 0, s[10:11]
	s_addc_u32 s31, s31, 0
	s_add_i32 s34, s53, s2
	global_load_lds_dwordx4 v[162:163], off
	v_lshl_add_u64 v[162:163], s[30:31], 0, v[132:133]
	s_mov_b32 m0, s34
	s_nop 0
	global_load_lds_dwordx4 v[162:163], off
	v_lshl_add_u64 v[162:163], s[30:31], 0, v[136:137]
	s_add_i32 m0, s34, 0x2000
	s_nop 0
	global_load_lds_dwordx4 v[162:163], off
	v_lshl_add_u64 v[162:163], v[220:221], 0, s[10:11]
	s_mov_b32 m0, s43
	s_nop 0
	global_load_lds_dwordx4 v[162:163], off
	v_lshl_add_u64 v[162:163], v[222:223], 0, s[10:11]
	s_mov_b32 m0, s44
	s_nop 0
	global_load_lds_dwordx4 v[162:163], off
	s_waitcnt vmcnt(8)
	s_waitcnt lgkmcnt(0)
	s_barrier
	s_nop 0
	s_waitcnt lgkmcnt(0)
	v_mfma_f32_16x16x32_bf16 v[62:65], v[142:145], v[186:189], v[62:65]
	v_mfma_f32_16x16x32_bf16 v[58:61], v[158:161], v[186:189], v[58:61]
	v_mfma_f32_16x16x32_bf16 v[46:49], v[142:145], v[194:197], v[46:49]
	v_mfma_f32_16x16x32_bf16 v[42:45], v[158:161], v[194:197], v[42:45]
	v_mfma_f32_16x16x32_bf16 v[30:33], v[142:145], v[202:205], v[30:33]
	v_mfma_f32_16x16x32_bf16 v[26:29], v[158:161], v[202:205], v[26:29]
	v_mfma_f32_16x16x32_bf16 v[14:17], v[142:145], v[210:213], v[14:17]
	v_mfma_f32_16x16x32_bf16 v[10:13], v[158:161], v[210:213], v[10:13]
	v_mfma_f32_16x16x32_bf16 v[62:65], v[154:157], v[190:193], v[62:65]
	v_mfma_f32_16x16x32_bf16 v[58:61], v[166:169], v[190:193], v[58:61]
	v_mfma_f32_16x16x32_bf16 v[46:49], v[154:157], v[198:201], v[46:49]
	v_mfma_f32_16x16x32_bf16 v[42:45], v[166:169], v[198:201], v[42:45]
	v_mfma_f32_16x16x32_bf16 v[30:33], v[154:157], v[206:209], v[30:33]
	v_mfma_f32_16x16x32_bf16 v[26:29], v[166:169], v[206:209], v[26:29]
	v_mfma_f32_16x16x32_bf16 v[14:17], v[154:157], v[214:217], v[14:17]
	v_mfma_f32_16x16x32_bf16 v[10:13], v[166:169], v[214:217], v[10:13]
	s_nop 0
	s_nop 0
	v_mfma_f32_16x16x32_bf16 v[54:57], v[170:173], v[186:189], v[54:57]
	v_mfma_f32_16x16x32_bf16 v[50:53], v[178:181], v[186:189], v[50:53]
	v_mfma_f32_16x16x32_bf16 v[38:41], v[170:173], v[194:197], v[38:41]
	v_mfma_f32_16x16x32_bf16 v[34:37], v[178:181], v[194:197], v[34:37]
	v_mfma_f32_16x16x32_bf16 v[22:25], v[170:173], v[202:205], v[22:25]
	v_mfma_f32_16x16x32_bf16 v[18:21], v[178:181], v[202:205], v[18:21]
	v_mfma_f32_16x16x32_bf16 v[6:9], v[170:173], v[210:213], v[6:9]
	v_mfma_f32_16x16x32_bf16 v[2:5], v[178:181], v[210:213], v[2:5]
	v_mfma_f32_16x16x32_bf16 v[54:57], v[174:177], v[190:193], v[54:57]
	v_mfma_f32_16x16x32_bf16 v[50:53], v[182:185], v[190:193], v[50:53]
	v_mfma_f32_16x16x32_bf16 v[38:41], v[174:177], v[198:201], v[38:41]
	v_mfma_f32_16x16x32_bf16 v[34:37], v[182:185], v[198:201], v[34:37]
	v_mfma_f32_16x16x32_bf16 v[22:25], v[174:177], v[206:209], v[22:25]
	v_mfma_f32_16x16x32_bf16 v[18:21], v[182:185], v[206:209], v[18:21]
	v_mfma_f32_16x16x32_bf16 v[6:9], v[174:177], v[214:217], v[6:9]
	v_mfma_f32_16x16x32_bf16 v[2:5], v[182:185], v[214:217], v[2:5]
	s_nop 0
	s_add_i32 s51, s51, 2
	s_add_u32 s28, s28, 0x100
	s_addc_u32 s29, s29, 0
	s_add_u32 s49, s49, 0x100
	s_addc_u32 s50, s50, 0
	s_cmp_gt_u32 s51, 5
	s_barrier
	s_cbranch_scc0 .LBB0_1220
	s_setprio 0
	s_lshl_b32 s98, s26, 8
	s_add_i32 s98, s98, s41
	v_add_u32_e32 v240, s98, v146
	s_lshl_b32 s98, s0, 8
	s_or_b32 s98, s98, s42
	v_lshl_add_u32 v241, v147, 3, s98
	v_lshlrev_b32_e32 v240, 12, v240
	v_lshl_add_u32 v240, v241, 1, v240
	global_load_dwordx4 v[168:171], v240, s[62:63]
	global_load_dwordx4 v[172:175], v240, s[62:63] offset:256
	v_add_u32_e32 v240, 0x10000, v240
	global_load_dwordx4 v[176:179], v240, s[62:63]
	global_load_dwordx4 v[180:183], v240, s[62:63] offset:256
	v_add_u32_e32 v240, 0x10000, v240
	global_load_dwordx4 v[184:187], v240, s[62:63]
	global_load_dwordx4 v[188:191], v240, s[62:63] offset:256
	v_add_u32_e32 v240, 0x10000, v240
	global_load_dwordx4 v[192:195], v240, s[62:63]
	global_load_dwordx4 v[196:199], v240, s[62:63] offset:256
	v_add_u32_e32 v240, 0x50000, v240
	global_load_dwordx4 v[200:203], v240, s[62:63]
	global_load_dwordx4 v[204:207], v240, s[62:63] offset:256
	v_add_u32_e32 v240, 0x10000, v240
	global_load_dwordx4 v[208:211], v240, s[62:63]
	global_load_dwordx4 v[212:215], v240, s[62:63] offset:256
	v_add_u32_e32 v240, 0x10000, v240
	global_load_dwordx4 v[216:219], v240, s[62:63]
	global_load_dwordx4 v[220:223], v240, s[62:63] offset:256
	v_add_u32_e32 v240, 0x10000, v240
	global_load_dwordx4 v[224:227], v240, s[62:63]
	global_load_dwordx4 v[232:235], v240, s[62:63] offset:256
	s_and_b64 vcc, exec, s[12:13]
	s_cbranch_vccz .LBB0_1223
	s_barrier

.Lsp_p10:
.LBB0_1337:
	ds_read_b128 v[142:145], v149
	ds_read_b128 v[154:157], v149 offset:1024
	ds_read_b128 v[158:161], v149 offset:2048
	ds_read_b128 v[166:169], v149 offset:3072
	ds_read_b128 v[170:173], v150
	ds_read_b128 v[174:177], v150 offset:1024
	ds_read_b128 v[178:181], v150 offset:2048
	ds_read_b128 v[182:185], v150 offset:3072
	s_add_u32 s30, s28, 0xfff80080
	s_addc_u32 s31, s29, -1
	s_cmp_eq_u32 s54, 28
	s_cselect_b32 s35, s17, s31
	s_cselect_b32 s34, s19, s30
	s_cselect_b32 s31, s50, s53
	s_cselect_b32 s30, s51, s52
	v_lshl_add_u64 v[162:163], s[28:29], 0, v[138:139]
	s_add_i32 m0, s25, 0xc000
	ds_read_b128 v[186:189], v151
	ds_read_b128 v[190:193], v151 offset:1024
	ds_read_b128 v[194:197], v151 offset:2048
	ds_read_b128 v[198:201], v151 offset:3072
	ds_read_b128 v[202:205], v151 offset:4096
	ds_read_b128 v[206:209], v151 offset:5120
	ds_read_b128 v[210:213], v151 offset:6144
	ds_read_b128 v[214:217], v151 offset:7168
	global_load_lds_dwordx4 v[162:163], off
	v_lshl_add_u64 v[162:163], s[28:29], 0, v[140:141]
	s_add_i32 m0, s25, 0xe000
	s_nop 0
	global_load_lds_dwordx4 v[162:163], off
	s_waitcnt vmcnt(8)
	s_waitcnt lgkmcnt(0)
	s_barrier
	s_nop 0
	s_waitcnt lgkmcnt(0)
	v_mfma_f32_16x16x32_bf16 v[122:125], v[142:145], v[186:189], v[122:125]
	v_mfma_f32_16x16x32_bf16 v[114:117], v[158:161], v[186:189], v[114:117]
	v_mfma_f32_16x16x32_bf16 v[106:109], v[142:145], v[194:197], v[106:109]
	v_mfma_f32_16x16x32_bf16 v[98:101], v[158:161], v[194:197], v[98:101]
	v_mfma_f32_16x16x32_bf16 v[90:93], v[142:145], v[202:205], v[90:93]
	v_mfma_f32_16x16x32_bf16 v[82:85], v[158:161], v[202:205], v[82:85]
	v_mfma_f32_16x16x32_bf16 v[74:77], v[142:145], v[210:213], v[74:77]
	v_mfma_f32_16x16x32_bf16 v[66:69], v[158:161], v[210:213], v[66:69]
	v_mfma_f32_16x16x32_bf16 v[122:125], v[154:157], v[190:193], v[122:125]
	v_mfma_f32_16x16x32_bf16 v[114:117], v[166:169], v[190:193], v[114:117]
	v_mfma_f32_16x16x32_bf16 v[106:109], v[154:157], v[198:201], v[106:109]
	v_mfma_f32_16x16x32_bf16 v[98:101], v[166:169], v[198:201], v[98:101]
	v_mfma_f32_16x16x32_bf16 v[90:93], v[154:157], v[206:209], v[90:93]
	v_mfma_f32_16x16x32_bf16 v[82:85], v[166:169], v[206:209], v[82:85]
	v_mfma_f32_16x16x32_bf16 v[74:77], v[154:157], v[214:217], v[74:77]
	v_mfma_f32_16x16x32_bf16 v[66:69], v[166:169], v[214:217], v[66:69]
	s_nop 0
	s_nop 0
	v_mfma_f32_16x16x32_bf16 v[126:129], v[170:173], v[186:189], v[126:129]
	v_mfma_f32_16x16x32_bf16 v[118:121], v[178:181], v[186:189], v[118:121]
	v_mfma_f32_16x16x32_bf16 v[110:113], v[170:173], v[194:197], v[110:113]
	v_mfma_f32_16x16x32_bf16 v[102:105], v[178:181], v[194:197], v[102:105]
	v_mfma_f32_16x16x32_bf16 v[94:97], v[170:173], v[202:205], v[94:97]
	v_mfma_f32_16x16x32_bf16 v[86:89], v[178:181], v[202:205], v[86:89]
	v_mfma_f32_16x16x32_bf16 v[78:81], v[170:173], v[210:213], v[78:81]
	v_mfma_f32_16x16x32_bf16 v[70:73], v[178:181], v[210:213], v[70:73]
	v_mfma_f32_16x16x32_bf16 v[126:129], v[174:177], v[190:193], v[126:129]
	v_mfma_f32_16x16x32_bf16 v[118:121], v[182:185], v[190:193], v[118:121]
	v_mfma_f32_16x16x32_bf16 v[110:113], v[174:177], v[198:201], v[110:113]
	v_mfma_f32_16x16x32_bf16 v[102:105], v[182:185], v[198:201], v[102:105]
	v_mfma_f32_16x16x32_bf16 v[94:97], v[174:177], v[206:209], v[94:97]
	v_mfma_f32_16x16x32_bf16 v[86:89], v[182:185], v[206:209], v[86:89]
	v_mfma_f32_16x16x32_bf16 v[78:81], v[174:177], v[214:217], v[78:81]
	v_mfma_f32_16x16x32_bf16 v[70:73], v[182:185], v[214:217], v[70:73]
	s_nop 0
	s_barrier
	s_add_i32 s55, s46, s36
	v_lshl_add_u64 v[162:163], s[30:31], 0, v[132:133]
	s_mov_b32 m0, s55
	ds_read_b128 v[186:189], v151 offset:16384
	ds_read_b128 v[190:193], v151 offset:17408
	ds_read_b128 v[194:197], v151 offset:18432
	ds_read_b128 v[198:201], v151 offset:19456
	ds_read_b128 v[202:205], v151 offset:20480
	ds_read_b128 v[206:209], v151 offset:21504
	ds_read_b128 v[210:213], v151 offset:22528
	ds_read_b128 v[214:217], v151 offset:23552
	global_load_lds_dwordx4 v[162:163], off
	s_add_i32 m0, s55, 0x2000
	s_add_u32 s56, s30, 0x80000
	v_lshl_add_u64 v[218:219], s[30:31], 0, v[136:137]
	s_addc_u32 s57, s31, 0
	s_add_i32 s55, s47, s36
	global_load_lds_dwordx4 v[218:219], off
	v_lshl_add_u64 v[220:221], s[56:57], 0, v[132:133]
	s_mov_b32 m0, s55
	v_lshl_add_u64 v[222:223], s[34:35], 0, v[134:135]
	global_load_lds_dwordx4 v[220:221], off
	v_lshl_add_u64 v[220:221], s[56:57], 0, v[136:137]
	s_add_i32 m0, s55, 0x2000
	s_nop 0
	global_load_lds_dwordx4 v[220:221], off
	v_lshl_add_u64 v[220:221], s[34:35], 0, v[130:131]
	s_mov_b32 m0, s25
	s_nop 0
	global_load_lds_dwordx4 v[220:221], off
	s_mov_b32 m0, s27
	s_nop 0
	global_load_lds_dwordx4 v[222:223], off
	s_waitcnt vmcnt(8)
	s_waitcnt lgkmcnt(0)
	s_barrier
	s_nop 0
	s_waitcnt lgkmcnt(0)
	v_mfma_f32_16x16x32_bf16 v[58:61], v[142:145], v[186:189], v[58:61]
	v_mfma_f32_16x16x32_bf16 v[50:53], v[158:161], v[186:189], v[50:53]
	v_mfma_f32_16x16x32_bf16 v[42:45], v[142:145], v[194:197], v[42:45]
	v_mfma_f32_16x16x32_bf16 v[34:37], v[158:161], v[194:197], v[34:37]
	v_mfma_f32_16x16x32_bf16 v[26:29], v[142:145], v[202:205], v[26:29]
	v_mfma_f32_16x16x32_bf16 v[18:21], v[158:161], v[202:205], v[18:21]
	v_mfma_f32_16x16x32_bf16 v[10:13], v[142:145], v[210:213], v[10:13]
	v_mfma_f32_16x16x32_bf16 v[2:5], v[158:161], v[210:213], v[2:5]
	v_mfma_f32_16x16x32_bf16 v[58:61], v[154:157], v[190:193], v[58:61]
	v_mfma_f32_16x16x32_bf16 v[50:53], v[166:169], v[190:193], v[50:53]
	v_mfma_f32_16x16x32_bf16 v[42:45], v[154:157], v[198:201], v[42:45]
	v_mfma_f32_16x16x32_bf16 v[34:37], v[166:169], v[198:201], v[34:37]
	v_mfma_f32_16x16x32_bf16 v[26:29], v[154:157], v[206:209], v[26:29]
	v_mfma_f32_16x16x32_bf16 v[18:21], v[166:169], v[206:209], v[18:21]
	v_mfma_f32_16x16x32_bf16 v[10:13], v[154:157], v[214:217], v[10:13]
	v_mfma_f32_16x16x32_bf16 v[2:5], v[166:169], v[214:217], v[2:5]
	s_nop 0
	s_nop 0
	v_mfma_f32_16x16x32_bf16 v[62:65], v[170:173], v[186:189], v[62:65]
	v_mfma_f32_16x16x32_bf16 v[54:57], v[178:181], v[186:189], v[54:57]
	v_mfma_f32_16x16x32_bf16 v[46:49], v[170:173], v[194:197], v[46:49]
	v_mfma_f32_16x16x32_bf16 v[38:41], v[178:181], v[194:197], v[38:41]
	v_mfma_f32_16x16x32_bf16 v[30:33], v[170:173], v[202:205], v[30:33]
	v_mfma_f32_16x16x32_bf16 v[22:25], v[178:181], v[202:205], v[22:25]
	v_mfma_f32_16x16x32_bf16 v[14:17], v[170:173], v[210:213], v[14:17]
	v_mfma_f32_16x16x32_bf16 v[6:9], v[178:181], v[210:213], v[6:9]
	v_mfma_f32_16x16x32_bf16 v[62:65], v[174:177], v[190:193], v[62:65]
	v_mfma_f32_16x16x32_bf16 v[54:57], v[182:185], v[190:193], v[54:57]
	v_mfma_f32_16x16x32_bf16 v[46:49], v[174:177], v[198:201], v[46:49]
	v_mfma_f32_16x16x32_bf16 v[38:41], v[182:185], v[198:201], v[38:41]
	v_mfma_f32_16x16x32_bf16 v[30:33], v[174:177], v[206:209], v[30:33]
	v_mfma_f32_16x16x32_bf16 v[22:25], v[182:185], v[206:209], v[22:25]
	v_mfma_f32_16x16x32_bf16 v[14:17], v[174:177], v[214:217], v[14:17]
	v_mfma_f32_16x16x32_bf16 v[6:9], v[182:185], v[214:217], v[6:9]
	s_nop 0
	s_barrier
	s_add_i32 s55, 0, 0x18000
	v_add_u32_e32 v153, s55, v148
	s_add_i32 s56, 0, 0x1c000
	ds_read_b128 v[142:145], v153
	ds_read_b128 v[154:157], v153 offset:1024
	ds_read_b128 v[158:161], v153 offset:2048
	ds_read_b128 v[166:169], v153 offset:3072
	v_add_u32_e32 v153, s56, v148
	ds_read_b128 v[170:173], v153
	ds_read_b128 v[174:177], v153 offset:1024
	ds_read_b128 v[178:181], v153 offset:2048
	ds_read_b128 v[182:185], v153 offset:3072
	s_add_u32 s34, s34, 0x80000
	s_addc_u32 s35, s35, 0
	s_mov_b32 m0, s37
	v_lshl_add_u64 v[224:225], s[34:35], 0, v[130:131]
	ds_read_b128 v[186:189], v151 offset:32768
	ds_read_b128 v[190:193], v151 offset:33792
	ds_read_b128 v[194:197], v151 offset:34816
	ds_read_b128 v[198:201], v151 offset:35840
	ds_read_b128 v[202:205], v151 offset:36864
	ds_read_b128 v[206:209], v151 offset:37888
	ds_read_b128 v[210:213], v151 offset:38912
	ds_read_b128 v[214:217], v151 offset:39936
	global_load_lds_dwordx4 v[224:225], off
	v_lshl_add_u64 v[224:225], s[34:35], 0, v[134:135]
	s_mov_b32 m0, s38
	s_nop 0
	global_load_lds_dwordx4 v[224:225], off
	s_waitcnt vmcnt(8)
	s_waitcnt lgkmcnt(0)
	s_barrier
	s_nop 0
	s_waitcnt lgkmcnt(0)
	v_mfma_f32_16x16x32_bf16 v[122:125], v[142:145], v[186:189], v[122:125]
	v_mfma_f32_16x16x32_bf16 v[114:117], v[158:161], v[186:189], v[114:117]
	v_mfma_f32_16x16x32_bf16 v[106:109], v[142:145], v[194:197], v[106:109]
	v_mfma_f32_16x16x32_bf16 v[98:101], v[158:161], v[194:197], v[98:101]
	v_mfma_f32_16x16x32_bf16 v[90:93], v[142:145], v[202:205], v[90:93]
	v_mfma_f32_16x16x32_bf16 v[82:85], v[158:161], v[202:205], v[82:85]
	v_mfma_f32_16x16x32_bf16 v[74:77], v[142:145], v[210:213], v[74:77]
	v_mfma_f32_16x16x32_bf16 v[66:69], v[158:161], v[210:213], v[66:69]
	v_mfma_f32_16x16x32_bf16 v[122:125], v[154:157], v[190:193], v[122:125]
	v_mfma_f32_16x16x32_bf16 v[114:117], v[166:169], v[190:193], v[114:117]
	v_mfma_f32_16x16x32_bf16 v[106:109], v[154:157], v[198:201], v[106:109]
	v_mfma_f32_16x16x32_bf16 v[98:101], v[166:169], v[198:201], v[98:101]
	v_mfma_f32_16x16x32_bf16 v[90:93], v[154:157], v[206:209], v[90:93]
	v_mfma_f32_16x16x32_bf16 v[82:85], v[166:169], v[206:209], v[82:85]
	v_mfma_f32_16x16x32_bf16 v[74:77], v[154:157], v[214:217], v[74:77]
	v_mfma_f32_16x16x32_bf16 v[66:69], v[166:169], v[214:217], v[66:69]
	s_nop 0
	s_nop 0
	v_mfma_f32_16x16x32_bf16 v[126:129], v[170:173], v[186:189], v[126:129]
	v_mfma_f32_16x16x32_bf16 v[118:121], v[178:181], v[186:189], v[118:121]
	v_mfma_f32_16x16x32_bf16 v[110:113], v[170:173], v[194:197], v[110:113]
	v_mfma_f32_16x16x32_bf16 v[102:105], v[178:181], v[194:197], v[102:105]
	v_mfma_f32_16x16x32_bf16 v[94:97], v[170:173], v[202:205], v[94:97]
	v_mfma_f32_16x16x32_bf16 v[86:89], v[178:181], v[202:205], v[86:89]
	v_mfma_f32_16x16x32_bf16 v[78:81], v[170:173], v[210:213], v[78:81]
	v_mfma_f32_16x16x32_bf16 v[70:73], v[178:181], v[210:213], v[70:73]
	v_mfma_f32_16x16x32_bf16 v[126:129], v[174:177], v[190:193], v[126:129]
	v_mfma_f32_16x16x32_bf16 v[118:121], v[182:185], v[190:193], v[118:121]
	v_mfma_f32_16x16x32_bf16 v[110:113], v[174:177], v[198:201], v[110:113]
	v_mfma_f32_16x16x32_bf16 v[102:105], v[182:185], v[198:201], v[102:105]
	v_mfma_f32_16x16x32_bf16 v[94:97], v[174:177], v[206:209], v[94:97]
	v_mfma_f32_16x16x32_bf16 v[86:89], v[182:185], v[206:209], v[86:89]
	v_mfma_f32_16x16x32_bf16 v[78:81], v[174:177], v[214:217], v[78:81]
	v_mfma_f32_16x16x32_bf16 v[70:73], v[182:185], v[214:217], v[70:73]
	s_nop 0
	s_barrier
	s_add_i32 s34, s55, s36
	v_lshl_add_u64 v[162:163], v[162:163], 0, s[12:13]
	s_mov_b32 m0, s34
	ds_read_b128 v[186:189], v151 offset:49152
	ds_read_b128 v[190:193], v151 offset:50176
	ds_read_b128 v[194:197], v151 offset:51200
	ds_read_b128 v[198:201], v151 offset:52224
	ds_read_b128 v[202:205], v151 offset:53248
	ds_read_b128 v[206:209], v151 offset:54272
	ds_read_b128 v[210:213], v151 offset:55296
	ds_read_b128 v[214:217], v151 offset:56320
	global_load_lds_dwordx4 v[162:163], off
	s_add_i32 m0, s34, 0x2000
	s_add_u32 s30, s30, 0x80080
	v_lshl_add_u64 v[162:163], v[218:219], 0, s[12:13]
	s_addc_u32 s31, s31, 0
	s_add_i32 s34, s56, s36
	global_load_lds_dwordx4 v[162:163], off
	v_lshl_add_u64 v[162:163], s[30:31], 0, v[132:133]
	s_mov_b32 m0, s34
	s_nop 0
	global_load_lds_dwordx4 v[162:163], off
	v_lshl_add_u64 v[162:163], s[30:31], 0, v[136:137]
	s_add_i32 m0, s34, 0x2000
	s_nop 0
	global_load_lds_dwordx4 v[162:163], off
	v_lshl_add_u64 v[162:163], v[220:221], 0, s[12:13]
	s_mov_b32 m0, s42
	s_nop 0
	global_load_lds_dwordx4 v[162:163], off
	v_lshl_add_u64 v[162:163], v[222:223], 0, s[12:13]
	s_mov_b32 m0, s43
	s_nop 0
	global_load_lds_dwordx4 v[162:163], off
	s_waitcnt vmcnt(8)
	s_waitcnt lgkmcnt(0)
	s_barrier
	s_nop 0
	s_waitcnt lgkmcnt(0)
	v_mfma_f32_16x16x32_bf16 v[58:61], v[142:145], v[186:189], v[58:61]
	v_mfma_f32_16x16x32_bf16 v[50:53], v[158:161], v[186:189], v[50:53]
	v_mfma_f32_16x16x32_bf16 v[42:45], v[142:145], v[194:197], v[42:45]
	v_mfma_f32_16x16x32_bf16 v[34:37], v[158:161], v[194:197], v[34:37]
	v_mfma_f32_16x16x32_bf16 v[26:29], v[142:145], v[202:205], v[26:29]
	v_mfma_f32_16x16x32_bf16 v[18:21], v[158:161], v[202:205], v[18:21]
	v_mfma_f32_16x16x32_bf16 v[10:13], v[142:145], v[210:213], v[10:13]
	v_mfma_f32_16x16x32_bf16 v[2:5], v[158:161], v[210:213], v[2:5]
	v_mfma_f32_16x16x32_bf16 v[58:61], v[154:157], v[190:193], v[58:61]
	v_mfma_f32_16x16x32_bf16 v[50:53], v[166:169], v[190:193], v[50:53]
	v_mfma_f32_16x16x32_bf16 v[42:45], v[154:157], v[198:201], v[42:45]
	v_mfma_f32_16x16x32_bf16 v[34:37], v[166:169], v[198:201], v[34:37]
	v_mfma_f32_16x16x32_bf16 v[26:29], v[154:157], v[206:209], v[26:29]
	v_mfma_f32_16x16x32_bf16 v[18:21], v[166:169], v[206:209], v[18:21]
	v_mfma_f32_16x16x32_bf16 v[10:13], v[154:157], v[214:217], v[10:13]
	v_mfma_f32_16x16x32_bf16 v[2:5], v[166:169], v[214:217], v[2:5]
	s_nop 0
	s_nop 0
	v_mfma_f32_16x16x32_bf16 v[62:65], v[170:173], v[186:189], v[62:65]
	v_mfma_f32_16x16x32_bf16 v[54:57], v[178:181], v[186:189], v[54:57]
	v_mfma_f32_16x16x32_bf16 v[46:49], v[170:173], v[194:197], v[46:49]
	v_mfma_f32_16x16x32_bf16 v[38:41], v[178:181], v[194:197], v[38:41]
	v_mfma_f32_16x16x32_bf16 v[30:33], v[170:173], v[202:205], v[30:33]
	v_mfma_f32_16x16x32_bf16 v[22:25], v[178:181], v[202:205], v[22:25]
	v_mfma_f32_16x16x32_bf16 v[14:17], v[170:173], v[210:213], v[14:17]
	v_mfma_f32_16x16x32_bf16 v[6:9], v[178:181], v[210:213], v[6:9]
	v_mfma_f32_16x16x32_bf16 v[62:65], v[174:177], v[190:193], v[62:65]
	v_mfma_f32_16x16x32_bf16 v[54:57], v[182:185], v[190:193], v[54:57]
	v_mfma_f32_16x16x32_bf16 v[46:49], v[174:177], v[198:201], v[46:49]
	v_mfma_f32_16x16x32_bf16 v[38:41], v[182:185], v[198:201], v[38:41]
	v_mfma_f32_16x16x32_bf16 v[30:33], v[174:177], v[206:209], v[30:33]
	v_mfma_f32_16x16x32_bf16 v[22:25], v[182:185], v[206:209], v[22:25]
	v_mfma_f32_16x16x32_bf16 v[14:17], v[174:177], v[214:217], v[14:17]
	v_mfma_f32_16x16x32_bf16 v[6:9], v[182:185], v[214:217], v[6:9]
	s_nop 0
	s_add_i32 s54, s54, 2
	s_add_u32 s28, s28, 0x100
	s_addc_u32 s29, s29, 0
	s_add_u32 s52, s52, 0x100
	s_addc_u32 s53, s53, 0
	s_cmp_gt_u32 s54, 29
	s_barrier
	s_cbranch_scc0 .LBB0_1337
	s_setprio 0
	v_mov_b32_e32 v142, v1
	v_mov_b32_e32 v153, v147
	v_mov_b32_e32 v143, v165
	v_mov_b32_e32 v144, v146
	s_lshl_b32 s17, s26, 8
	s_add_i32 s17, s17, s40
	v_add_u32_e32 v142, s17, v144
	v_ashrrev_i32_e32 v143, 31, v142
	v_lshl_add_u64 v[144:145], v[142:143], 2, s[10:11]
	global_load_dword v229, v[144:145], off
	global_load_dword v230, v[144:145], off offset:64
	global_load_dword v231, v[144:145], off offset:128
	global_load_dword v232, v[144:145], off offset:192
	global_load_dword v233, v[144:145], off offset:512
	global_load_dword v234, v[144:145], off offset:576
	global_load_dword v235, v[144:145], off offset:640
	global_load_dword v236, v[144:145], off offset:704
	s_and_b64 vcc, exec, s[14:15]
	s_cbranch_vccz .LBB0_1340
	s_barrier

.Lsp_p11:
.LBB0_1449:
	ds_read_b128 v[140:143], v167
	ds_read_b128 v[144:147], v167 offset:1024
	ds_read_b128 v[148:151], v167 offset:2048
	ds_read_b128 v[152:155], v167 offset:3072
	ds_read_b128 v[156:159], v168
	ds_read_b128 v[172:175], v168 offset:1024
	ds_read_b128 v[176:179], v168 offset:2048
	ds_read_b128 v[180:183], v168 offset:3072
	s_add_u32 s20, s0, 0xffea0080
	s_addc_u32 s21, s1, -1
	s_cmpk_eq_i32 s52, 0x54
	s_cselect_b32 s23, s25, s21
	s_cselect_b32 s22, s47, s20
	s_cselect_b32 s21, s48, s51
	s_cselect_b32 s20, s49, s50
	v_lshl_add_u64 v[160:161], s[0:1], 0, v[136:137]
	s_add_i32 m0, s29, 0xc000
	ds_read_b128 v[184:187], v169
	ds_read_b128 v[188:191], v169 offset:1024
	ds_read_b128 v[192:195], v169 offset:2048
	ds_read_b128 v[196:199], v169 offset:3072
	ds_read_b128 v[200:203], v169 offset:4096
	ds_read_b128 v[204:207], v169 offset:5120
	ds_read_b128 v[208:211], v169 offset:6144
	ds_read_b128 v[212:215], v169 offset:7168
	global_load_lds_dwordx4 v[160:161], off
	v_lshl_add_u64 v[160:161], s[0:1], 0, v[138:139]
	s_add_i32 m0, s29, 0xe000
	s_nop 0
	global_load_lds_dwordx4 v[160:161], off
	s_waitcnt vmcnt(8)
	s_waitcnt lgkmcnt(0)
	s_barrier
	s_nop 0
	s_waitcnt lgkmcnt(0)
	v_mfma_f32_16x16x32_bf16 v[124:127], v[140:143], v[184:187], v[124:127]
	v_mfma_f32_16x16x32_bf16 v[120:123], v[148:151], v[184:187], v[120:123]
	v_mfma_f32_16x16x32_bf16 v[108:111], v[140:143], v[192:195], v[108:111]
	v_mfma_f32_16x16x32_bf16 v[104:107], v[148:151], v[192:195], v[104:107]
	v_mfma_f32_16x16x32_bf16 v[92:95], v[140:143], v[200:203], v[92:95]
	v_mfma_f32_16x16x32_bf16 v[88:91], v[148:151], v[200:203], v[88:91]
	v_mfma_f32_16x16x32_bf16 v[76:79], v[140:143], v[208:211], v[76:79]
	v_mfma_f32_16x16x32_bf16 v[72:75], v[148:151], v[208:211], v[72:75]
	v_mfma_f32_16x16x32_bf16 v[124:127], v[144:147], v[188:191], v[124:127]
	v_mfma_f32_16x16x32_bf16 v[120:123], v[152:155], v[188:191], v[120:123]
	v_mfma_f32_16x16x32_bf16 v[108:111], v[144:147], v[196:199], v[108:111]
	v_mfma_f32_16x16x32_bf16 v[104:107], v[152:155], v[196:199], v[104:107]
	v_mfma_f32_16x16x32_bf16 v[92:95], v[144:147], v[204:207], v[92:95]
	v_mfma_f32_16x16x32_bf16 v[88:91], v[152:155], v[204:207], v[88:91]
	v_mfma_f32_16x16x32_bf16 v[76:79], v[144:147], v[212:215], v[76:79]
	v_mfma_f32_16x16x32_bf16 v[72:75], v[152:155], v[212:215], v[72:75]
	s_nop 0
	s_nop 0
	v_mfma_f32_16x16x32_bf16 v[116:119], v[156:159], v[184:187], v[116:119]
	v_mfma_f32_16x16x32_bf16 v[112:115], v[176:179], v[184:187], v[112:115]
	v_mfma_f32_16x16x32_bf16 v[100:103], v[156:159], v[192:195], v[100:103]
	v_mfma_f32_16x16x32_bf16 v[96:99], v[176:179], v[192:195], v[96:99]
	v_mfma_f32_16x16x32_bf16 v[84:87], v[156:159], v[200:203], v[84:87]
	v_mfma_f32_16x16x32_bf16 v[80:83], v[176:179], v[200:203], v[80:83]
	v_mfma_f32_16x16x32_bf16 v[68:71], v[156:159], v[208:211], v[68:71]
	v_mfma_f32_16x16x32_bf16 v[64:67], v[176:179], v[208:211], v[64:67]
	v_mfma_f32_16x16x32_bf16 v[116:119], v[172:175], v[188:191], v[116:119]
	v_mfma_f32_16x16x32_bf16 v[112:115], v[180:183], v[188:191], v[112:115]
	v_mfma_f32_16x16x32_bf16 v[100:103], v[172:175], v[196:199], v[100:103]
	v_mfma_f32_16x16x32_bf16 v[96:99], v[180:183], v[196:199], v[96:99]
	v_mfma_f32_16x16x32_bf16 v[84:87], v[172:175], v[204:207], v[84:87]
	v_mfma_f32_16x16x32_bf16 v[80:83], v[180:183], v[204:207], v[80:83]
	v_mfma_f32_16x16x32_bf16 v[68:71], v[172:175], v[212:215], v[68:71]
	v_mfma_f32_16x16x32_bf16 v[64:67], v[180:183], v[212:215], v[64:67]
	s_nop 0
	s_barrier
	s_add_i32 s53, s42, s28
	v_lshl_add_u64 v[160:161], s[20:21], 0, v[130:131]
	s_mov_b32 m0, s53
	ds_read_b128 v[184:187], v169 offset:16384
	ds_read_b128 v[188:191], v169 offset:17408
	ds_read_b128 v[192:195], v169 offset:18432
	ds_read_b128 v[196:199], v169 offset:19456
	ds_read_b128 v[200:203], v169 offset:20480
	ds_read_b128 v[204:207], v169 offset:21504
	ds_read_b128 v[208:211], v169 offset:22528
	ds_read_b128 v[212:215], v169 offset:23552
	global_load_lds_dwordx4 v[160:161], off
	s_add_i32 m0, s53, 0x2000
	s_add_u32 s54, s20, 0x160000
	v_lshl_add_u64 v[216:217], s[20:21], 0, v[134:135]
	s_addc_u32 s55, s21, 0
	s_add_i32 s53, s43, s28
	global_load_lds_dwordx4 v[216:217], off
	v_lshl_add_u64 v[218:219], s[54:55], 0, v[130:131]
	s_mov_b32 m0, s53
	v_lshl_add_u64 v[220:221], s[22:23], 0, v[132:133]
	global_load_lds_dwordx4 v[218:219], off
	v_lshl_add_u64 v[218:219], s[54:55], 0, v[134:135]
	s_add_i32 m0, s53, 0x2000
	s_nop 0
	global_load_lds_dwordx4 v[218:219], off
	v_lshl_add_u64 v[218:219], s[22:23], 0, v[128:129]
	s_mov_b32 m0, s29
	s_nop 0
	global_load_lds_dwordx4 v[218:219], off
	s_mov_b32 m0, s30
	s_nop 0
	global_load_lds_dwordx4 v[220:221], off
	s_waitcnt vmcnt(8)
	s_waitcnt lgkmcnt(0)
	s_barrier
	s_nop 0
	s_waitcnt lgkmcnt(0)
	v_mfma_f32_16x16x32_bf16 v[60:63], v[140:143], v[184:187], v[60:63]
	v_mfma_f32_16x16x32_bf16 v[56:59], v[148:151], v[184:187], v[56:59]
	v_mfma_f32_16x16x32_bf16 v[44:47], v[140:143], v[192:195], v[44:47]
	v_mfma_f32_16x16x32_bf16 v[40:43], v[148:151], v[192:195], v[40:43]
	v_mfma_f32_16x16x32_bf16 v[28:31], v[140:143], v[200:203], v[28:31]
	v_mfma_f32_16x16x32_bf16 v[24:27], v[148:151], v[200:203], v[24:27]
	v_mfma_f32_16x16x32_bf16 v[12:15], v[140:143], v[208:211], v[12:15]
	v_mfma_f32_16x16x32_bf16 v[8:11], v[148:151], v[208:211], v[8:11]
	v_mfma_f32_16x16x32_bf16 v[60:63], v[144:147], v[188:191], v[60:63]
	v_mfma_f32_16x16x32_bf16 v[56:59], v[152:155], v[188:191], v[56:59]
	v_mfma_f32_16x16x32_bf16 v[44:47], v[144:147], v[196:199], v[44:47]
	v_mfma_f32_16x16x32_bf16 v[40:43], v[152:155], v[196:199], v[40:43]
	v_mfma_f32_16x16x32_bf16 v[28:31], v[144:147], v[204:207], v[28:31]
	v_mfma_f32_16x16x32_bf16 v[24:27], v[152:155], v[204:207], v[24:27]
	v_mfma_f32_16x16x32_bf16 v[12:15], v[144:147], v[212:215], v[12:15]
	v_mfma_f32_16x16x32_bf16 v[8:11], v[152:155], v[212:215], v[8:11]
	s_nop 0
	s_nop 0
	v_mfma_f32_16x16x32_bf16 v[52:55], v[156:159], v[184:187], v[52:55]
	v_mfma_f32_16x16x32_bf16 v[48:51], v[176:179], v[184:187], v[48:51]
	v_mfma_f32_16x16x32_bf16 v[36:39], v[156:159], v[192:195], v[36:39]
	v_mfma_f32_16x16x32_bf16 v[32:35], v[176:179], v[192:195], v[32:35]
	v_mfma_f32_16x16x32_bf16 v[20:23], v[156:159], v[200:203], v[20:23]
	v_mfma_f32_16x16x32_bf16 v[16:19], v[176:179], v[200:203], v[16:19]
	v_mfma_f32_16x16x32_bf16 v[4:7], v[156:159], v[208:211], v[4:7]
	v_mfma_f32_16x16x32_bf16 v[0:3], v[176:179], v[208:211], v[0:3]
	v_mfma_f32_16x16x32_bf16 v[52:55], v[172:175], v[188:191], v[52:55]
	v_mfma_f32_16x16x32_bf16 v[48:51], v[180:183], v[188:191], v[48:51]
	v_mfma_f32_16x16x32_bf16 v[36:39], v[172:175], v[196:199], v[36:39]
	v_mfma_f32_16x16x32_bf16 v[32:35], v[180:183], v[196:199], v[32:35]
	v_mfma_f32_16x16x32_bf16 v[20:23], v[172:175], v[204:207], v[20:23]
	v_mfma_f32_16x16x32_bf16 v[16:19], v[180:183], v[204:207], v[16:19]
	v_mfma_f32_16x16x32_bf16 v[4:7], v[172:175], v[212:215], v[4:7]
	v_mfma_f32_16x16x32_bf16 v[0:3], v[180:183], v[212:215], v[0:3]
	s_nop 0
	s_barrier
	s_add_i32 s53, 0, 0x18000
	s_add_i32 s54, 0, 0x1c000
	v_add_u32_e32 v152, s53, v166
	v_add_u32_e32 v180, s54, v166
	ds_read_b128 v[140:143], v152
	ds_read_b128 v[144:147], v152 offset:1024
	ds_read_b128 v[148:151], v152 offset:2048
	ds_read_b128 v[152:155], v152 offset:3072
	ds_read_b128 v[156:159], v180
	ds_read_b128 v[172:175], v180 offset:1024
	ds_read_b128 v[176:179], v180 offset:2048
	ds_read_b128 v[180:183], v180 offset:3072
	s_add_u32 s22, s22, 0x160000
	s_addc_u32 s23, s23, 0
	s_mov_b32 m0, s31
	v_lshl_add_u64 v[222:223], s[22:23], 0, v[128:129]
	ds_read_b128 v[184:187], v169 offset:32768
	ds_read_b128 v[188:191], v169 offset:33792
	ds_read_b128 v[192:195], v169 offset:34816
	ds_read_b128 v[196:199], v169 offset:35840
	ds_read_b128 v[200:203], v169 offset:36864
	ds_read_b128 v[204:207], v169 offset:37888
	ds_read_b128 v[208:211], v169 offset:38912
	ds_read_b128 v[212:215], v169 offset:39936
	global_load_lds_dwordx4 v[222:223], off
	v_lshl_add_u64 v[222:223], s[22:23], 0, v[132:133]
	s_mov_b32 m0, s33
	s_nop 0
	global_load_lds_dwordx4 v[222:223], off
	s_waitcnt vmcnt(8)
	s_waitcnt lgkmcnt(0)
	s_barrier
	s_nop 0
	s_waitcnt lgkmcnt(0)
	v_mfma_f32_16x16x32_bf16 v[124:127], v[140:143], v[184:187], v[124:127]
	v_mfma_f32_16x16x32_bf16 v[120:123], v[148:151], v[184:187], v[120:123]
	v_mfma_f32_16x16x32_bf16 v[108:111], v[140:143], v[192:195], v[108:111]
	v_mfma_f32_16x16x32_bf16 v[104:107], v[148:151], v[192:195], v[104:107]
	v_mfma_f32_16x16x32_bf16 v[92:95], v[140:143], v[200:203], v[92:95]
	v_mfma_f32_16x16x32_bf16 v[88:91], v[148:151], v[200:203], v[88:91]
	v_mfma_f32_16x16x32_bf16 v[76:79], v[140:143], v[208:211], v[76:79]
	v_mfma_f32_16x16x32_bf16 v[72:75], v[148:151], v[208:211], v[72:75]
	v_mfma_f32_16x16x32_bf16 v[124:127], v[144:147], v[188:191], v[124:127]
	v_mfma_f32_16x16x32_bf16 v[120:123], v[152:155], v[188:191], v[120:123]
	v_mfma_f32_16x16x32_bf16 v[108:111], v[144:147], v[196:199], v[108:111]
	v_mfma_f32_16x16x32_bf16 v[104:107], v[152:155], v[196:199], v[104:107]
	v_mfma_f32_16x16x32_bf16 v[92:95], v[144:147], v[204:207], v[92:95]
	v_mfma_f32_16x16x32_bf16 v[88:91], v[152:155], v[204:207], v[88:91]
	v_mfma_f32_16x16x32_bf16 v[76:79], v[144:147], v[212:215], v[76:79]
	v_mfma_f32_16x16x32_bf16 v[72:75], v[152:155], v[212:215], v[72:75]
	s_nop 0
	s_nop 0
	v_mfma_f32_16x16x32_bf16 v[116:119], v[156:159], v[184:187], v[116:119]
	v_mfma_f32_16x16x32_bf16 v[112:115], v[176:179], v[184:187], v[112:115]
	v_mfma_f32_16x16x32_bf16 v[100:103], v[156:159], v[192:195], v[100:103]
	v_mfma_f32_16x16x32_bf16 v[96:99], v[176:179], v[192:195], v[96:99]
	v_mfma_f32_16x16x32_bf16 v[84:87], v[156:159], v[200:203], v[84:87]
	v_mfma_f32_16x16x32_bf16 v[80:83], v[176:179], v[200:203], v[80:83]
	v_mfma_f32_16x16x32_bf16 v[68:71], v[156:159], v[208:211], v[68:71]
	v_mfma_f32_16x16x32_bf16 v[64:67], v[176:179], v[208:211], v[64:67]
	v_mfma_f32_16x16x32_bf16 v[116:119], v[172:175], v[188:191], v[116:119]
	v_mfma_f32_16x16x32_bf16 v[112:115], v[180:183], v[188:191], v[112:115]
	v_mfma_f32_16x16x32_bf16 v[100:103], v[172:175], v[196:199], v[100:103]
	v_mfma_f32_16x16x32_bf16 v[96:99], v[180:183], v[196:199], v[96:99]
	v_mfma_f32_16x16x32_bf16 v[84:87], v[172:175], v[204:207], v[84:87]
	v_mfma_f32_16x16x32_bf16 v[80:83], v[180:183], v[204:207], v[80:83]
	v_mfma_f32_16x16x32_bf16 v[68:71], v[172:175], v[212:215], v[68:71]
	v_mfma_f32_16x16x32_bf16 v[64:67], v[180:183], v[212:215], v[64:67]
	s_nop 0
	s_barrier
	s_add_i32 s22, s53, s28
	v_lshl_add_u64 v[160:161], v[160:161], 0, s[8:9]
	s_mov_b32 m0, s22
	ds_read_b128 v[184:187], v169 offset:49152
	ds_read_b128 v[188:191], v169 offset:50176
	ds_read_b128 v[192:195], v169 offset:51200
	ds_read_b128 v[196:199], v169 offset:52224
	ds_read_b128 v[200:203], v169 offset:53248
	ds_read_b128 v[204:207], v169 offset:54272
	ds_read_b128 v[208:211], v169 offset:55296
	ds_read_b128 v[212:215], v169 offset:56320
	global_load_lds_dwordx4 v[160:161], off
	s_add_i32 m0, s22, 0x2000
	s_add_u32 s20, s20, 0x160080
	v_lshl_add_u64 v[160:161], v[216:217], 0, s[8:9]
	s_addc_u32 s21, s21, 0
	s_add_i32 s22, s54, s28
	global_load_lds_dwordx4 v[160:161], off
	v_lshl_add_u64 v[160:161], s[20:21], 0, v[130:131]
	s_mov_b32 m0, s22
	s_nop 0
	global_load_lds_dwordx4 v[160:161], off
	v_lshl_add_u64 v[160:161], s[20:21], 0, v[134:135]
	s_add_i32 m0, s22, 0x2000
	s_nop 0
	global_load_lds_dwordx4 v[160:161], off
	v_lshl_add_u64 v[160:161], v[218:219], 0, s[8:9]
	s_mov_b32 m0, s39
	s_nop 0
	global_load_lds_dwordx4 v[160:161], off
	v_lshl_add_u64 v[160:161], v[220:221], 0, s[8:9]
	s_mov_b32 m0, s40
	s_nop 0
	global_load_lds_dwordx4 v[160:161], off
	s_waitcnt vmcnt(8)
	s_waitcnt lgkmcnt(0)
	s_barrier
	s_nop 0
	s_waitcnt lgkmcnt(0)
	v_mfma_f32_16x16x32_bf16 v[60:63], v[140:143], v[184:187], v[60:63]
	v_mfma_f32_16x16x32_bf16 v[56:59], v[148:151], v[184:187], v[56:59]
	v_mfma_f32_16x16x32_bf16 v[44:47], v[140:143], v[192:195], v[44:47]
	v_mfma_f32_16x16x32_bf16 v[40:43], v[148:151], v[192:195], v[40:43]
	v_mfma_f32_16x16x32_bf16 v[28:31], v[140:143], v[200:203], v[28:31]
	v_mfma_f32_16x16x32_bf16 v[24:27], v[148:151], v[200:203], v[24:27]
	v_mfma_f32_16x16x32_bf16 v[12:15], v[140:143], v[208:211], v[12:15]
	v_mfma_f32_16x16x32_bf16 v[8:11], v[148:151], v[208:211], v[8:11]
	v_mfma_f32_16x16x32_bf16 v[60:63], v[144:147], v[188:191], v[60:63]
	v_mfma_f32_16x16x32_bf16 v[56:59], v[152:155], v[188:191], v[56:59]
	v_mfma_f32_16x16x32_bf16 v[44:47], v[144:147], v[196:199], v[44:47]
	v_mfma_f32_16x16x32_bf16 v[40:43], v[152:155], v[196:199], v[40:43]
	v_mfma_f32_16x16x32_bf16 v[28:31], v[144:147], v[204:207], v[28:31]
	v_mfma_f32_16x16x32_bf16 v[24:27], v[152:155], v[204:207], v[24:27]
	v_mfma_f32_16x16x32_bf16 v[12:15], v[144:147], v[212:215], v[12:15]
	v_mfma_f32_16x16x32_bf16 v[8:11], v[152:155], v[212:215], v[8:11]
	s_nop 0
	s_nop 0
	v_mfma_f32_16x16x32_bf16 v[52:55], v[156:159], v[184:187], v[52:55]
	v_mfma_f32_16x16x32_bf16 v[48:51], v[176:179], v[184:187], v[48:51]
	v_mfma_f32_16x16x32_bf16 v[36:39], v[156:159], v[192:195], v[36:39]
	v_mfma_f32_16x16x32_bf16 v[32:35], v[176:179], v[192:195], v[32:35]
	v_mfma_f32_16x16x32_bf16 v[20:23], v[156:159], v[200:203], v[20:23]
	v_mfma_f32_16x16x32_bf16 v[16:19], v[176:179], v[200:203], v[16:19]
	v_mfma_f32_16x16x32_bf16 v[4:7], v[156:159], v[208:211], v[4:7]
	v_mfma_f32_16x16x32_bf16 v[0:3], v[176:179], v[208:211], v[0:3]
	v_mfma_f32_16x16x32_bf16 v[52:55], v[172:175], v[188:191], v[52:55]
	v_mfma_f32_16x16x32_bf16 v[48:51], v[180:183], v[188:191], v[48:51]
	v_mfma_f32_16x16x32_bf16 v[36:39], v[172:175], v[196:199], v[36:39]
	v_mfma_f32_16x16x32_bf16 v[32:35], v[180:183], v[196:199], v[32:35]
	v_mfma_f32_16x16x32_bf16 v[20:23], v[172:175], v[204:207], v[20:23]
	v_mfma_f32_16x16x32_bf16 v[16:19], v[180:183], v[204:207], v[16:19]
	v_mfma_f32_16x16x32_bf16 v[4:7], v[172:175], v[212:215], v[4:7]
	v_mfma_f32_16x16x32_bf16 v[0:3], v[180:183], v[212:215], v[0:3]
	s_nop 0
	s_add_i32 s52, s52, 2
	s_add_u32 s0, s0, 0x100
	s_addc_u32 s1, s1, 0
	s_add_u32 s50, s50, 0x100
	s_addc_u32 s51, s51, 0
	s_cmpk_gt_u32 s52, 0x55
	s_barrier
	s_cbranch_scc0 .LBB0_1449
	s_setprio 0
	s_and_b64 vcc, exec, s[10:11]
	s_cbranch_vccz .LBB0_1452
	s_barrier
